# memattn: waves 4-7 issue their Q-fragment loads after the K-staging barrier, so the two waves of each SIMD run the QK (MFMA) and softmax (VALU) stretches of the score sweeps out of phase
# speedup vs baseline: 1.0055x; 1.0055x over previous
.LBB0_123:
	s_add_i32 s4, s5, s6
	s_ashr_i32 s5, s4, 31
	s_lshr_b32 s5, s5, 29
	s_add_i32 s5, s4, s5
	s_ashr_i32 s6, s5, 3
	s_lshl_b32 s6, s6, 1
	s_sub_i32 s7, 64, s6
	s_min_i32 s7, s7, 2
	s_abs_i32 s9, s7
	v_cvt_f32_u32_e32 v0, s9
	s_sub_i32 s10, 0, s9
	s_and_b32 s5, s5, -8
	s_sub_i32 s5, s4, s5
	v_rcp_iflag_f32_e32 v0, v0
	s_abs_i32 s8, s5
	s_xor_b32 s4, s5, s7
	s_ashr_i32 s4, s4, 31
	v_mul_f32_e32 v0, 0x4f7ffffe, v0
	v_cvt_u32_f32_e32 v0, v0
	v_mov_b32_e32 v8, v245
	v_cmp_lt_i32_e32 vcc, v234, v228
	v_readfirstlane_b32 s11, v0
	s_mul_i32 s10, s10, s11
	s_mul_hi_u32 s10, s11, s10
	s_add_i32 s11, s11, s10
	s_mul_hi_u32 s10, s8, s11
	s_mul_i32 s11, s10, s9
	s_sub_i32 s8, s8, s11
	s_add_i32 s11, s10, 1
	s_sub_i32 s12, s8, s9
	s_cmp_ge_u32 s8, s9
	s_cselect_b32 s10, s11, s10
	s_cselect_b32 s8, s12, s8
	s_add_i32 s11, s10, 1
	s_cmp_ge_u32 s8, s9
	s_cselect_b32 s8, s11, s10
	s_xor_b32 s8, s8, s4
	s_sub_i32 s4, s8, s4
	s_mul_i32 s7, s4, s7
	s_sub_i32 s5, s5, s7
	s_add_i32 s5, s6, s5
	s_ashr_i32 s6, s5, 31
	s_lshr_b32 s6, s6, 28
	s_add_i32 s6, s5, s6
	s_ashr_i32 s30, s6, 4
	s_and_b32 s6, s6, 0xfffff0
	s_sub_i32 s5, s5, s6
	s_lshl_b32 s10, s30, 8
	s_lshl_b32 s7, s5, 8
	s_ashr_i32 s11, s10, 31
	s_ashr_i32 s31, s30, 31
	s_ashr_i32 s8, s7, 31
	s_lshl_b64 s[10:11], s[10:11], 12
	s_add_u32 s6, s33, s10
	s_waitcnt lgkmcnt(0)
	v_ashrrev_i32_e32 v2, 6, v8
	s_addc_u32 s9, s40, s11
	s_lshl_b32 s4, s4, 8
	v_bfe_u32 v72, v8, 5, 1
	v_lshlrev_b32_e32 v0, 5, v2
	s_ashr_i32 s5, s4, 31
	s_lshl_b64 s[28:29], s[4:5], 1
	v_readfirstlane_b32 s4, v2
	v_or_b32_e32 v2, v0, v72
	v_and_b32_e32 v9, 31, v8
	v_lshrrev_b32_e32 v10, 5, v8
	s_add_u32 s36, s6, s28
	v_ashrrev_i32_e32 v3, 31, v2
	s_addc_u32 s37, s9, s29
	v_lshlrev_b64 v[4:5], 12, v[2:3]
	v_bitop3_b32 v3, v10, v9, 1 bitop3:0x6c
	v_lshl_add_u64 v[4:5], s[36:37], 0, v[4:5]
	v_lshlrev_b32_e32 v96, 4, v3
	v_lshl_add_u64 v[4:5], v[4:5], 0, v[96:97]
	s_lshl_b32 s9, s4, 14
	s_add_i32 s4, s9, 0
	s_mov_b32 s5, m0
	s_mov_b32 m0, s4
	s_nop 0
	global_load_lds_dwordx4 v[4:5], off
	s_mov_b32 m0, s5
	v_or_b32_e32 v4, 2, v2
	v_ashrrev_i32_e32 v5, 31, v4
	v_lshlrev_b64 v[6:7], 12, v[4:5]
	v_bitop3_b32 v3, v4, v9, 3 bitop3:0x6c
	v_lshl_add_u64 v[6:7], s[36:37], 0, v[6:7]
	v_lshlrev_b32_e32 v4, 4, v3
	v_mov_b32_e32 v5, v97
	v_lshl_add_u64 v[4:5], v[6:7], 0, v[4:5]
	s_add_i32 s5, 0, 0x400
	s_add_i32 s4, s9, s5
	s_mov_b32 s6, m0
	s_mov_b32 m0, s4
	s_nop 0
	global_load_lds_dwordx4 v[4:5], off
	s_mov_b32 m0, s6
	v_or_b32_e32 v4, 4, v2
	v_ashrrev_i32_e32 v5, 31, v4
	v_lshlrev_b64 v[6:7], 12, v[4:5]
	v_bitop3_b32 v3, v4, v9, 5 bitop3:0x6c
	v_lshl_add_u64 v[6:7], s[36:37], 0, v[6:7]
	v_lshlrev_b32_e32 v4, 4, v3
	v_mov_b32_e32 v5, v97
	v_lshl_add_u64 v[4:5], v[6:7], 0, v[4:5]
	s_add_i32 s6, 0, 0x800
	s_add_i32 s4, s9, s6
	s_mov_b32 s10, m0
	s_mov_b32 m0, s4
	s_nop 0
	global_load_lds_dwordx4 v[4:5], off
	s_mov_b32 m0, s10
	v_or_b32_e32 v4, 6, v2
	v_ashrrev_i32_e32 v5, 31, v4
	v_lshlrev_b64 v[6:7], 12, v[4:5]
	v_bitop3_b32 v3, v4, v9, 7 bitop3:0x6c
	v_lshl_add_u64 v[6:7], s[36:37], 0, v[6:7]
	v_lshlrev_b32_e32 v4, 4, v3
	v_mov_b32_e32 v5, v97
	v_lshl_add_u64 v[4:5], v[6:7], 0, v[4:5]
	s_add_i32 s4, s9, s18
	s_mov_b32 s10, m0
	s_mov_b32 m0, s4
	s_nop 0
	global_load_lds_dwordx4 v[4:5], off
	s_mov_b32 m0, s10
	v_or_b32_e32 v4, 8, v2
	v_ashrrev_i32_e32 v5, 31, v4
	v_lshlrev_b64 v[6:7], 12, v[4:5]
	v_bitop3_b32 v3, v4, v9, 9 bitop3:0x6c
	v_lshl_add_u64 v[6:7], s[36:37], 0, v[6:7]
	v_lshlrev_b32_e32 v4, 4, v3
	v_mov_b32_e32 v5, v97
	v_lshl_add_u64 v[4:5], v[6:7], 0, v[4:5]
	s_add_i32 s4, 0, 0x1000
	s_add_i32 s10, s9, s4
	s_mov_b32 s11, m0
	s_mov_b32 m0, s10
	s_nop 0
	global_load_lds_dwordx4 v[4:5], off
	s_mov_b32 m0, s11
	v_or_b32_e32 v4, 10, v2
	v_ashrrev_i32_e32 v5, 31, v4
	v_lshlrev_b64 v[6:7], 12, v[4:5]
	v_bitop3_b32 v3, v4, v9, 11 bitop3:0x6c
	v_lshl_add_u64 v[6:7], s[36:37], 0, v[6:7]
	v_lshlrev_b32_e32 v4, 4, v3
	v_mov_b32_e32 v5, v97
	v_lshl_add_u64 v[4:5], v[6:7], 0, v[4:5]
	s_add_i32 s10, s9, s19
	s_mov_b32 s11, m0
	s_mov_b32 m0, s10
	s_nop 0
	global_load_lds_dwordx4 v[4:5], off
	s_mov_b32 m0, s11
	v_or_b32_e32 v4, 12, v2
	v_ashrrev_i32_e32 v5, 31, v4
	v_lshlrev_b64 v[6:7], 12, v[4:5]
	v_bitop3_b32 v3, v4, v9, 13 bitop3:0x6c
	v_lshl_add_u64 v[6:7], s[36:37], 0, v[6:7]
	v_lshlrev_b32_e32 v4, 4, v3
	v_mov_b32_e32 v5, v97
	v_lshl_add_u64 v[4:5], v[6:7], 0, v[4:5]
	s_add_i32 s10, s9, s41
	s_mov_b32 s11, m0
	s_mov_b32 m0, s10
	s_nop 0
	global_load_lds_dwordx4 v[4:5], off
	s_mov_b32 m0, s11
	v_or_b32_e32 v4, 14, v2
	v_ashrrev_i32_e32 v5, 31, v4
	v_lshlrev_b64 v[6:7], 12, v[4:5]
	v_bitop3_b32 v3, v4, v9, 15 bitop3:0x6c
	v_lshl_add_u64 v[6:7], s[36:37], 0, v[6:7]
	v_lshlrev_b32_e32 v4, 4, v3
	v_mov_b32_e32 v5, v97
	v_lshl_add_u64 v[4:5], v[6:7], 0, v[4:5]
	s_add_i32 s10, s9, s42
	s_mov_b32 s11, m0
	s_mov_b32 m0, s10
	s_nop 0
	global_load_lds_dwordx4 v[4:5], off
	s_mov_b32 m0, s11
	v_or_b32_e32 v4, 16, v2
	v_ashrrev_i32_e32 v5, 31, v4
	v_lshlrev_b64 v[4:5], 12, v[4:5]
	v_lshl_add_u64 v[4:5], s[36:37], 0, v[4:5]
	v_lshl_add_u64 v[4:5], v[4:5], 0, v[96:97]
	s_add_i32 s10, s9, s43
	s_mov_b32 s11, m0
	s_mov_b32 m0, s10
	s_nop 0
	global_load_lds_dwordx4 v[4:5], off
	s_mov_b32 m0, s11
	v_or_b32_e32 v4, 18, v2
	v_ashrrev_i32_e32 v5, 31, v4
	v_lshlrev_b64 v[6:7], 12, v[4:5]
	v_bitop3_b32 v3, v4, v9, 3 bitop3:0x6c
	v_lshl_add_u64 v[6:7], s[36:37], 0, v[6:7]
	v_lshlrev_b32_e32 v96, 4, v3
	v_lshl_add_u64 v[4:5], v[6:7], 0, v[96:97]
	s_add_i32 s10, s9, s44
	s_mov_b32 s11, m0
	s_mov_b32 m0, s10
	s_nop 0
	global_load_lds_dwordx4 v[4:5], off
	s_mov_b32 m0, s11
	v_or_b32_e32 v4, 20, v2
	v_ashrrev_i32_e32 v5, 31, v4
	v_lshlrev_b64 v[6:7], 12, v[4:5]
	v_bitop3_b32 v3, v4, v9, 5 bitop3:0x6c
	v_lshl_add_u64 v[6:7], s[36:37], 0, v[6:7]
	v_lshlrev_b32_e32 v96, 4, v3
	v_lshl_add_u64 v[4:5], v[6:7], 0, v[96:97]
	s_add_i32 s10, s9, s45
	s_mov_b32 s11, m0
	s_mov_b32 m0, s10
	s_nop 0
	global_load_lds_dwordx4 v[4:5], off
	s_mov_b32 m0, s11
	v_or_b32_e32 v4, 22, v2
	v_ashrrev_i32_e32 v5, 31, v4
	v_lshlrev_b64 v[6:7], 12, v[4:5]
	v_bitop3_b32 v3, v4, v9, 7 bitop3:0x6c
	v_lshl_add_u64 v[6:7], s[36:37], 0, v[6:7]
	v_lshlrev_b32_e32 v96, 4, v3
	v_lshl_add_u64 v[4:5], v[6:7], 0, v[96:97]
	s_add_i32 s10, s9, s46
	s_mov_b32 s11, m0
	s_mov_b32 m0, s10
	s_nop 0
	global_load_lds_dwordx4 v[4:5], off
	s_mov_b32 m0, s11
	v_or_b32_e32 v4, 24, v2
	v_ashrrev_i32_e32 v5, 31, v4
	v_lshlrev_b64 v[6:7], 12, v[4:5]
	v_bitop3_b32 v3, v4, v9, 9 bitop3:0x6c
	v_lshl_add_u64 v[6:7], s[36:37], 0, v[6:7]
	v_lshlrev_b32_e32 v96, 4, v3
	v_lshl_add_u64 v[4:5], v[6:7], 0, v[96:97]
	s_add_i32 s10, s9, s47
	s_mov_b32 s11, m0
	s_mov_b32 m0, s10
	s_nop 0
	global_load_lds_dwordx4 v[4:5], off
	s_mov_b32 m0, s11
	v_or_b32_e32 v4, 26, v2
	v_ashrrev_i32_e32 v5, 31, v4
	v_lshlrev_b64 v[6:7], 12, v[4:5]
	v_bitop3_b32 v3, v4, v9, 11 bitop3:0x6c
	v_lshl_add_u64 v[6:7], s[36:37], 0, v[6:7]
	v_lshlrev_b32_e32 v96, 4, v3
	v_lshl_add_u64 v[4:5], v[6:7], 0, v[96:97]
	s_add_i32 s10, s9, s48
	s_mov_b32 s11, m0
	s_mov_b32 m0, s10
	s_nop 0
	global_load_lds_dwordx4 v[4:5], off
	s_mov_b32 m0, s11
	v_or_b32_e32 v4, 28, v2
	v_ashrrev_i32_e32 v5, 31, v4
	v_lshlrev_b64 v[6:7], 12, v[4:5]
	v_bitop3_b32 v3, v4, v9, 13 bitop3:0x6c
	v_lshl_add_u64 v[6:7], s[36:37], 0, v[6:7]
	v_lshlrev_b32_e32 v96, 4, v3
	v_or_b32_e32 v2, 30, v2
	v_lshl_add_u64 v[4:5], v[6:7], 0, v[96:97]
	v_ashrrev_i32_e32 v3, 31, v2
	s_add_i32 s10, s9, s49
	s_mov_b32 s11, m0
	s_mov_b32 m0, s10
	s_nop 0
	global_load_lds_dwordx4 v[4:5], off
	s_mov_b32 m0, s11
	v_lshlrev_b64 v[4:5], 12, v[2:3]
	v_bitop3_b32 v2, v2, v9, 15 bitop3:0x6c
	v_lshl_add_u64 v[4:5], s[36:37], 0, v[4:5]
	v_lshlrev_b32_e32 v96, 4, v2
	v_lshl_add_u64 v[2:3], v[4:5], 0, v[96:97]
	s_add_i32 s9, s9, s50
	s_mov_b32 s10, m0
	s_mov_b32 m0, s9
	s_nop 0
	global_load_lds_dwordx4 v[2:3], off
	s_mov_b32 m0, s10
	s_lshl_b64 s[10:11], s[30:31], 12
	s_add_u32 s38, s10, s7
	v_ashrrev_i32_e32 v1, 31, v0
	s_addc_u32 s39, s11, s8
	v_lshl_add_u64 v[0:1], s[38:39], 0, v[0:1]
	v_or_b32_e32 v0, v0, v9
	v_lshlrev_b64 v[0:1], 11, v[0:1]
	v_lshl_add_u64 v[0:1], s[24:25], 0, v[0:1]
	v_lshl_add_u64 v[0:1], v[0:1], 0, s[28:29]
	v_lshlrev_b32_e32 v96, 4, v72
	v_lshl_add_u64 v[0:1], v[0:1], 0, v[96:97]
	v_mov_b32_e32 v184, v0
	v_mov_b32_e32 v185, v1
	s_bitcmp1_b32 s9, 16
	s_cbranch_scc1 .Lma_q_late
	global_load_dwordx4 v[142:145], v[0:1], off
	global_load_dwordx4 v[138:141], v[0:1], off offset:32
	global_load_dwordx4 v[134:137], v[0:1], off offset:64
	global_load_dwordx4 v[130:133], v[0:1], off offset:96
	global_load_dwordx4 v[126:129], v[0:1], off offset:128
	global_load_dwordx4 v[122:125], v[0:1], off offset:160
	global_load_dwordx4 v[118:121], v[0:1], off offset:192
	global_load_dwordx4 v[114:117], v[0:1], off offset:224
	global_load_dwordx4 v[60:63], v[0:1], off offset:256
	global_load_dwordx4 v[56:59], v[0:1], off offset:288
	global_load_dwordx4 v[52:55], v[0:1], off offset:320
	global_load_dwordx4 v[48:51], v[0:1], off offset:352
	global_load_dwordx4 v[44:47], v[0:1], off offset:384
	global_load_dwordx4 v[40:43], v[0:1], off offset:416
	global_load_dwordx4 v[36:39], v[0:1], off offset:448
	global_load_dwordx4 v[32:35], v[0:1], off offset:480
.Lma_q_late:
	v_and_b32_e32 v73, 15, v8
	v_bitop3_b32 v0, v10, v73, 1 bitop3:0x6c
	v_lshl_add_u32 v162, v9, 9, 0
	v_lshlrev_b32_e32 v161, 4, v0
	v_add_u32_e32 v89, v162, v161
	s_waitcnt vmcnt(0)
	s_barrier
	s_bitcmp0_b32 s9, 16
	s_cbranch_scc1 .Lma_q_done
	global_load_dwordx4 v[142:145], v[184:185], off
	global_load_dwordx4 v[138:141], v[184:185], off offset:32
	global_load_dwordx4 v[134:137], v[184:185], off offset:64
	global_load_dwordx4 v[130:133], v[184:185], off offset:96
	global_load_dwordx4 v[126:129], v[184:185], off offset:128
	global_load_dwordx4 v[122:125], v[184:185], off offset:160
	global_load_dwordx4 v[118:121], v[184:185], off offset:192
	global_load_dwordx4 v[114:117], v[184:185], off offset:224
	global_load_dwordx4 v[60:63], v[184:185], off offset:256
	global_load_dwordx4 v[56:59], v[184:185], off offset:288
	global_load_dwordx4 v[52:55], v[184:185], off offset:320
	global_load_dwordx4 v[48:51], v[184:185], off offset:352
	global_load_dwordx4 v[44:47], v[184:185], off offset:384
	global_load_dwordx4 v[40:43], v[184:185], off offset:416
	global_load_dwordx4 v[36:39], v[184:185], off offset:448
	global_load_dwordx4 v[32:35], v[184:185], off offset:480
.Lma_q_done:
	ds_read_b128 v[0:3], v89
	ds_read_b128 v[16:19], v89 offset:16384
	s_waitcnt vmcnt(0) lgkmcnt(0)
	v_mfma_f32_32x32x16_bf16 v[0:15], v[0:3], v[142:145], 0
	v_bitop3_b32 v64, v72, v73, 2 bitop3:0x36
	v_lshlrev_b32_e32 v160, 4, v64
	v_add_u32_e32 v86, v162, v160
	ds_read_b128 v[64:67], v86
	ds_read_b128 v[68:71], v86 offset:16384
	s_add_i32 s2, s2, 1
	s_waitcnt lgkmcnt(2)
	v_mfma_f32_32x32x16_bf16 v[16:31], v[16:19], v[142:145], 0
	s_waitcnt vmcnt(14) lgkmcnt(1)
	v_mfma_f32_32x32x16_bf16 v[0:15], v[64:67], v[138:141], v[0:15]
	v_bitop3_b32 v64, v72, v73, 4 bitop3:0x36
	v_lshlrev_b32_e32 v159, 4, v64
	v_add_u32_e32 v87, v162, v159
	s_waitcnt lgkmcnt(0)
	v_mfma_f32_32x32x16_bf16 v[16:31], v[68:71], v[138:141], v[16:31]
	ds_read_b128 v[64:67], v87
	ds_read_b128 v[68:71], v87 offset:16384
	s_waitcnt vmcnt(13) lgkmcnt(1)
	v_mfma_f32_32x32x16_bf16 v[0:15], v[64:67], v[134:137], v[0:15]
	v_bitop3_b32 v64, v72, v73, 6 bitop3:0x36
	v_lshlrev_b32_e32 v158, 4, v64
	v_add_u32_e32 v88, v162, v158
	s_waitcnt lgkmcnt(0)
	v_mfma_f32_32x32x16_bf16 v[16:31], v[68:71], v[134:137], v[16:31]
	ds_read_b128 v[64:67], v88
	ds_read_b128 v[68:71], v88 offset:16384
	s_waitcnt vmcnt(12) lgkmcnt(1)
	v_mfma_f32_32x32x16_bf16 v[0:15], v[64:67], v[130:133], v[0:15]
	v_bitop3_b32 v64, v72, v73, 8 bitop3:0x36
	v_lshlrev_b32_e32 v157, 4, v64
	v_add_u32_e32 v90, v162, v157
	s_waitcnt lgkmcnt(0)
	v_mfma_f32_32x32x16_bf16 v[16:31], v[68:71], v[130:133], v[16:31]
	ds_read_b128 v[64:67], v90
	ds_read_b128 v[68:71], v90 offset:16384
	s_waitcnt vmcnt(11) lgkmcnt(1)
	v_mfma_f32_32x32x16_bf16 v[0:15], v[64:67], v[126:129], v[0:15]
	v_bitop3_b32 v64, v72, v73, 10 bitop3:0x36
	v_lshlrev_b32_e32 v156, 4, v64
	v_add_u32_e32 v91, v162, v156
	s_waitcnt lgkmcnt(0)
	v_mfma_f32_32x32x16_bf16 v[16:31], v[68:71], v[126:129], v[16:31]
	ds_read_b128 v[64:67], v91
	ds_read_b128 v[68:71], v91 offset:16384
	s_waitcnt vmcnt(10) lgkmcnt(1)
	v_mfma_f32_32x32x16_bf16 v[0:15], v[64:67], v[122:125], v[0:15]
	v_bitop3_b32 v64, v72, v73, 12 bitop3:0x36
	v_lshlrev_b32_e32 v155, 4, v64
	v_add_u32_e32 v92, v162, v155
	s_waitcnt lgkmcnt(0)
	v_mfma_f32_32x32x16_bf16 v[16:31], v[68:71], v[122:125], v[16:31]
	ds_read_b128 v[64:67], v92
	ds_read_b128 v[68:71], v92 offset:16384
	s_waitcnt vmcnt(9) lgkmcnt(1)
	v_mfma_f32_32x32x16_bf16 v[0:15], v[64:67], v[118:121], v[0:15]
	v_bitop3_b32 v64, v72, v73, 14 bitop3:0x36
	v_lshlrev_b32_e32 v154, 4, v64
	v_add_u32_e32 v93, v162, v154
	s_waitcnt lgkmcnt(0)
	v_mfma_f32_32x32x16_bf16 v[16:31], v[68:71], v[118:121], v[16:31]
	ds_read_b128 v[64:67], v93
	ds_read_b128 v[68:71], v93 offset:16384
	s_waitcnt vmcnt(8) lgkmcnt(1)
	v_mfma_f32_32x32x16_bf16 v[0:15], v[64:67], v[114:117], v[0:15]
	v_bitop3_b32 v64, v72, v73, 16 bitop3:0x36
	v_lshlrev_b32_e32 v153, 4, v64
	v_add_u32_e32 v95, v162, v153
	s_waitcnt lgkmcnt(0)
	v_mfma_f32_32x32x16_bf16 v[16:31], v[68:71], v[114:117], v[16:31]
	ds_read_b128 v[64:67], v95
	ds_read_b128 v[68:71], v95 offset:16384
	s_waitcnt vmcnt(7) lgkmcnt(1)
	v_mfma_f32_32x32x16_bf16 v[0:15], v[64:67], v[60:63], v[0:15]
	v_bitop3_b32 v64, v72, v73, 18 bitop3:0x36
	v_lshlrev_b32_e32 v152, 4, v64
	v_add_u32_e32 v94, v162, v152
	s_waitcnt lgkmcnt(0)
	v_mfma_f32_32x32x16_bf16 v[16:31], v[68:71], v[60:63], v[16:31]
	ds_read_b128 v[64:67], v94
	ds_read_b128 v[68:71], v94 offset:16384
	s_waitcnt vmcnt(6) lgkmcnt(1)
	v_mfma_f32_32x32x16_bf16 v[0:15], v[64:67], v[56:59], v[0:15]
	v_bitop3_b32 v64, v72, v73, 20 bitop3:0x36
	v_lshlrev_b32_e32 v151, 4, v64
	v_add_u32_e32 v85, v162, v151
	s_waitcnt lgkmcnt(0)
	v_mfma_f32_32x32x16_bf16 v[16:31], v[68:71], v[56:59], v[16:31]
	ds_read_b128 v[64:67], v85
	ds_read_b128 v[68:71], v85 offset:16384
	s_waitcnt vmcnt(5) lgkmcnt(1)
	v_mfma_f32_32x32x16_bf16 v[0:15], v[64:67], v[52:55], v[0:15]
	v_bitop3_b32 v64, v72, v73, 22 bitop3:0x36
	v_lshlrev_b32_e32 v150, 4, v64
	v_add_u32_e32 v84, v162, v150
	s_waitcnt lgkmcnt(0)
	v_mfma_f32_32x32x16_bf16 v[16:31], v[68:71], v[52:55], v[16:31]
	ds_read_b128 v[64:67], v84
	ds_read_b128 v[68:71], v84 offset:16384
	s_waitcnt vmcnt(4) lgkmcnt(1)
	v_mfma_f32_32x32x16_bf16 v[0:15], v[64:67], v[48:51], v[0:15]
	v_bitop3_b32 v64, v72, v73, 24 bitop3:0x36
	v_lshlrev_b32_e32 v149, 4, v64
	v_add_u32_e32 v83, v162, v149
	s_waitcnt lgkmcnt(0)
	v_mfma_f32_32x32x16_bf16 v[16:31], v[68:71], v[48:51], v[16:31]
	ds_read_b128 v[64:67], v83
	ds_read_b128 v[68:71], v83 offset:16384
	s_waitcnt vmcnt(3) lgkmcnt(1)
	v_mfma_f32_32x32x16_bf16 v[0:15], v[64:67], v[44:47], v[0:15]
	v_bitop3_b32 v64, v72, v73, 26 bitop3:0x36
	v_lshlrev_b32_e32 v148, 4, v64
	v_add_u32_e32 v82, v162, v148
	s_waitcnt lgkmcnt(0)
	v_mfma_f32_32x32x16_bf16 v[16:31], v[68:71], v[44:47], v[16:31]
	ds_read_b128 v[64:67], v82
	ds_read_b128 v[68:71], v82 offset:16384
	s_waitcnt vmcnt(2) lgkmcnt(1)
	v_mfma_f32_32x32x16_bf16 v[0:15], v[64:67], v[40:43], v[0:15]
	v_bitop3_b32 v64, v72, v73, 28 bitop3:0x36
	v_lshlrev_b32_e32 v147, 4, v64
	v_add_u32_e32 v81, v162, v147
	s_waitcnt lgkmcnt(0)
	v_mfma_f32_32x32x16_bf16 v[16:31], v[68:71], v[40:43], v[16:31]
	ds_read_b128 v[64:67], v81
	ds_read_b128 v[68:71], v81 offset:16384
	s_waitcnt vmcnt(1) lgkmcnt(1)
	v_mfma_f32_32x32x16_bf16 v[0:15], v[64:67], v[36:39], v[0:15]
	v_bitop3_b32 v64, v72, v73, 30 bitop3:0x36
	v_lshlrev_b32_e32 v146, 4, v64
	v_add_u32_e32 v80, v162, v146
	s_waitcnt lgkmcnt(0)
	v_mfma_f32_32x32x16_bf16 v[16:31], v[68:71], v[36:39], v[16:31]
	ds_read_b128 v[64:67], v80
	ds_read_b128 v[68:71], v80 offset:16384
	s_waitcnt vmcnt(0) lgkmcnt(1)
	v_mfma_f32_32x32x16_bf16 v[0:15], v[64:67], v[32:35], v[0:15]
	s_waitcnt lgkmcnt(0)
	v_mfma_f32_32x32x16_bf16 v[16:31], v[68:71], v[32:35], v[16:31]
	s_nop 9
	v_max_f32_e32 v65, v0, v0
	v_max_f32_e32 v66, v1, v1
	v_max_f32_e32 v67, v3, v3
	v_max_f32_e32 v64, v16, v16
	v_max_f32_e32 v64, v65, v64
	v_max_f32_e32 v65, v17, v17
	v_max_f32_e32 v65, v66, v65
	v_max3_f32 v64, v64, s35, v65
	v_max_f32_e32 v65, v18, v18
	v_max_f32_e32 v66, v2, v2
	v_max_f32_e32 v65, v66, v65
	v_max_f32_e32 v66, v19, v19
	v_max_f32_e32 v66, v67, v66
	v_max3_f32 v64, v64, v65, v66
	v_max_f32_e32 v65, v20, v20
	v_max_f32_e32 v66, v4, v4
	v_max_f32_e32 v65, v66, v65
	v_max_f32_e32 v66, v21, v21
	v_max_f32_e32 v67, v5, v5
	v_max_f32_e32 v66, v67, v66
	v_max3_f32 v64, v64, v65, v66
	v_max_f32_e32 v65, v22, v22
	v_max_f32_e32 v66, v6, v6
	v_max_f32_e32 v65, v66, v65
	v_max_f32_e32 v66, v23, v23
	v_max_f32_e32 v67, v7, v7
	v_max_f32_e32 v66, v67, v66
	v_max3_f32 v64, v64, v65, v66
	v_max_f32_e32 v65, v24, v24
	v_max_f32_e32 v66, v8, v8
	v_max_f32_e32 v65, v66, v65
	v_max_f32_e32 v66, v25, v25
	v_max_f32_e32 v67, v9, v9
	v_max_f32_e32 v66, v67, v66
	v_max3_f32 v64, v64, v65, v66
	v_max_f32_e32 v65, v26, v26
	v_max_f32_e32 v66, v10, v10
	v_max_f32_e32 v65, v66, v65
	v_max_f32_e32 v66, v27, v27
	v_max_f32_e32 v67, v11, v11
	v_max_f32_e32 v66, v67, v66
	v_max3_f32 v64, v64, v65, v66
	v_max_f32_e32 v65, v28, v28
	v_max_f32_e32 v66, v12, v12
	v_max_f32_e32 v65, v66, v65
	v_max_f32_e32 v66, v29, v29
	v_max_f32_e32 v67, v13, v13
	v_max_f32_e32 v66, v67, v66
	v_max3_f32 v64, v64, v65, v66
	v_max_f32_e32 v65, v30, v30
	v_max_f32_e32 v66, v14, v14
	v_max_f32_e32 v65, v66, v65
	v_max_f32_e32 v66, v31, v31
	v_max_f32_e32 v67, v15, v15
	v_max_f32_e32 v66, v67, v66
	v_max3_f32 v64, v64, v65, v66
	v_mov_b32_e32 v65, v64
	s_nop 1
	v_permlane32_swap_b32_e32 v64, v65
	v_max_f32_e32 v65, v65, v65
	v_max_f32_e32 v64, v64, v64
	v_max_f32_e32 v96, v64, v65
	v_sub_f32_e32 v0, v0, v96
	v_sub_f32_e32 v16, v16, v96
	v_exp_f32_e32 v0, v0
	v_exp_f32_e32 v16, v16
	v_sub_f32_e32 v1, v1, v96
	v_sub_f32_e32 v17, v17, v96
	v_exp_f32_e32 v1, v1
	v_exp_f32_e32 v17, v17
	v_sub_f32_e32 v2, v2, v96
	v_sub_f32_e32 v18, v18, v96
	v_exp_f32_e32 v2, v2
	v_exp_f32_e32 v18, v18
	v_sub_f32_e32 v3, v3, v96
	v_sub_f32_e32 v19, v19, v96
	v_exp_f32_e32 v3, v3
	v_exp_f32_e32 v19, v19
	v_sub_f32_e32 v4, v4, v96
	v_sub_f32_e32 v20, v20, v96
	v_add_f32_e32 v98, v16, v0
	v_exp_f32_e32 v4, v4
	v_exp_f32_e32 v20, v20
	v_sub_f32_e32 v5, v5, v96
	v_sub_f32_e32 v21, v21, v96
	v_add_f32_e32 v99, v17, v1
	v_exp_f32_e32 v5, v5
	v_exp_f32_e32 v21, v21
	v_sub_f32_e32 v6, v6, v96
	v_sub_f32_e32 v22, v22, v96
	v_cvt_pk_bf16_f32 v76, v0, v1
	v_add_f32_e32 v0, 0, v98
	v_add_f32_e32 v100, v18, v2
	v_exp_f32_e32 v6, v6
	v_exp_f32_e32 v22, v22
	v_sub_f32_e32 v7, v7, v96
	v_sub_f32_e32 v23, v23, v96
	v_add_f32_e32 v0, v99, v0
	v_add_f32_e32 v101, v19, v3
	v_exp_f32_e32 v7, v7
	v_exp_f32_e32 v23, v23
	v_sub_f32_e32 v8, v8, v96
	v_sub_f32_e32 v24, v24, v96
	v_add_f32_e32 v0, v100, v0
	v_add_f32_e32 v102, v20, v4
	v_exp_f32_e32 v8, v8
	v_exp_f32_e32 v24, v24
	v_sub_f32_e32 v9, v9, v96
	v_sub_f32_e32 v25, v25, v96
	v_add_f32_e32 v0, v101, v0
	v_add_f32_e32 v103, v21, v5
	v_exp_f32_e32 v9, v9
	v_exp_f32_e32 v25, v25
	v_sub_f32_e32 v10, v10, v96
	v_sub_f32_e32 v26, v26, v96
	v_add_f32_e32 v0, v102, v0
	v_add_f32_e32 v104, v22, v6
	v_exp_f32_e32 v10, v10
	v_exp_f32_e32 v26, v26
	v_sub_f32_e32 v11, v11, v96
	v_sub_f32_e32 v27, v27, v96
	v_add_f32_e32 v0, v103, v0
	v_add_f32_e32 v105, v23, v7
	v_exp_f32_e32 v11, v11
	v_exp_f32_e32 v27, v27
	v_sub_f32_e32 v12, v12, v96
	v_sub_f32_e32 v28, v28, v96
	v_add_f32_e32 v0, v104, v0
	v_add_f32_e32 v106, v24, v8
	v_exp_f32_e32 v12, v12
	v_exp_f32_e32 v28, v28
	v_sub_f32_e32 v13, v13, v96
	v_sub_f32_e32 v29, v29, v96
	v_add_f32_e32 v0, v105, v0
	v_add_f32_e32 v107, v25, v9
	v_exp_f32_e32 v13, v13
	v_exp_f32_e32 v29, v29
	v_sub_f32_e32 v14, v14, v96
	v_sub_f32_e32 v30, v30, v96
	v_add_f32_e32 v0, v106, v0
	v_add_f32_e32 v108, v26, v10
	v_exp_f32_e32 v14, v14
	v_exp_f32_e32 v30, v30
	v_sub_f32_e32 v15, v15, v96
	v_sub_f32_e32 v31, v31, v96
	v_add_f32_e32 v0, v107, v0
	v_add_f32_e32 v109, v27, v11
	v_exp_f32_e32 v15, v15
	v_exp_f32_e32 v31, v31
	v_add_f32_e32 v0, v108, v0
	v_add_f32_e32 v110, v28, v12
	v_add_f32_e32 v0, v109, v0
	v_add_f32_e32 v111, v29, v13
	v_add_f32_e32 v0, v110, v0
	v_add_f32_e32 v112, v30, v14
	v_add_f32_e32 v0, v111, v0
	v_add_f32_e32 v113, v31, v15
	v_add_f32_e32 v0, v112, v0
	v_cvt_pk_bf16_f32 v77, v2, v3
	v_cvt_pk_bf16_f32 v78, v4, v5
	v_cvt_pk_bf16_f32 v79, v6, v7
	v_add_f32_e32 v98, v113, v0
	ds_read_b128 v[0:3], v89 offset:32768
	ds_read_b128 v[4:7], v89 offset:49152
	v_cvt_pk_bf16_f32 v68, v16, v17
	v_cvt_pk_bf16_f32 v69, v18, v19
	v_cvt_pk_bf16_f32 v70, v20, v21
	v_cvt_pk_bf16_f32 v71, v22, v23
	v_cvt_pk_bf16_f32 v72, v8, v9
	v_cvt_pk_bf16_f32 v73, v10, v11
	v_cvt_pk_bf16_f32 v74, v12, v13
	v_cvt_pk_bf16_f32 v75, v14, v15
	v_cvt_pk_bf16_f32 v64, v24, v25
	v_cvt_pk_bf16_f32 v65, v26, v27
	v_cvt_pk_bf16_f32 v66, v28, v29
	v_cvt_pk_bf16_f32 v67, v30, v31
	s_waitcnt lgkmcnt(1)
	v_mfma_f32_32x32x16_bf16 v[16:31], v[0:3], v[142:145], 0
	ds_read_b128 v[100:103], v86 offset:32768
	ds_read_b128 v[104:107], v86 offset:49152
	s_waitcnt lgkmcnt(2)
	v_mfma_f32_32x32x16_bf16 v[0:15], v[4:7], v[142:145], 0
	s_waitcnt lgkmcnt(1)
	v_mfma_f32_32x32x16_bf16 v[16:31], v[100:103], v[138:141], v[16:31]
	s_waitcnt lgkmcnt(0)
	v_mfma_f32_32x32x16_bf16 v[0:15], v[104:107], v[138:141], v[0:15]
	ds_read_b128 v[100:103], v87 offset:32768
	ds_read_b128 v[104:107], v87 offset:49152
	s_waitcnt lgkmcnt(1)
	v_mfma_f32_32x32x16_bf16 v[16:31], v[100:103], v[134:137], v[16:31]
	ds_read_b128 v[100:103], v88 offset:32768
	ds_read_b128 v[86:89], v88 offset:49152
	s_waitcnt lgkmcnt(2)
	v_mfma_f32_32x32x16_bf16 v[0:15], v[104:107], v[134:137], v[0:15]
	s_waitcnt lgkmcnt(1)
	v_mfma_f32_32x32x16_bf16 v[16:31], v[100:103], v[130:133], v[16:31]
	s_waitcnt lgkmcnt(0)
	v_mfma_f32_32x32x16_bf16 v[0:15], v[86:89], v[130:133], v[0:15]
	ds_read_b128 v[86:89], v90 offset:32768
	ds_read_b128 v[100:103], v90 offset:49152
	s_waitcnt lgkmcnt(1)
	v_mfma_f32_32x32x16_bf16 v[16:31], v[86:89], v[126:129], v[16:31]
	s_waitcnt lgkmcnt(0)
	v_mfma_f32_32x32x16_bf16 v[0:15], v[100:103], v[126:129], v[0:15]
	ds_read_b128 v[86:89], v91 offset:32768
	ds_read_b128 v[100:103], v91 offset:49152
	s_waitcnt lgkmcnt(1)
	v_mfma_f32_32x32x16_bf16 v[16:31], v[86:89], v[122:125], v[16:31]
	s_waitcnt lgkmcnt(0)
	v_mfma_f32_32x32x16_bf16 v[0:15], v[100:103], v[122:125], v[0:15]
	ds_read_b128 v[86:89], v92 offset:32768
	ds_read_b128 v[100:103], v92 offset:49152
	s_waitcnt lgkmcnt(1)
	v_mfma_f32_32x32x16_bf16 v[16:31], v[86:89], v[118:121], v[16:31]
	ds_read_b128 v[86:89], v93 offset:32768
	ds_read_b128 v[90:93], v93 offset:49152
	s_waitcnt lgkmcnt(2)
	v_mfma_f32_32x32x16_bf16 v[0:15], v[100:103], v[118:121], v[0:15]
	s_waitcnt lgkmcnt(1)
	v_mfma_f32_32x32x16_bf16 v[16:31], v[86:89], v[114:117], v[16:31]
	s_waitcnt lgkmcnt(0)
	v_mfma_f32_32x32x16_bf16 v[0:15], v[90:93], v[114:117], v[0:15]
	ds_read_b128 v[86:89], v95 offset:32768
	ds_read_b128 v[90:93], v95 offset:49152
	s_waitcnt lgkmcnt(1)
	v_mfma_f32_32x32x16_bf16 v[16:31], v[86:89], v[60:63], v[16:31]
	s_waitcnt lgkmcnt(0)
	v_mfma_f32_32x32x16_bf16 v[0:15], v[90:93], v[60:63], v[0:15]
	ds_read_b128 v[86:89], v94 offset:32768
	ds_read_b128 v[90:93], v94 offset:49152
	s_waitcnt lgkmcnt(1)
	v_mfma_f32_32x32x16_bf16 v[16:31], v[86:89], v[56:59], v[16:31]
	s_waitcnt lgkmcnt(0)
	v_mfma_f32_32x32x16_bf16 v[0:15], v[90:93], v[56:59], v[0:15]
	ds_read_b128 v[86:89], v85 offset:32768
	ds_read_b128 v[90:93], v85 offset:49152
	s_waitcnt lgkmcnt(1)
	v_mfma_f32_32x32x16_bf16 v[16:31], v[86:89], v[52:55], v[16:31]
	s_waitcnt lgkmcnt(0)
	v_mfma_f32_32x32x16_bf16 v[0:15], v[90:93], v[52:55], v[0:15]
	ds_read_b128 v[86:89], v84 offset:32768
	ds_read_b128 v[90:93], v84 offset:49152
	s_waitcnt lgkmcnt(1)
	v_mfma_f32_32x32x16_bf16 v[16:31], v[86:89], v[48:51], v[16:31]
	s_waitcnt lgkmcnt(0)
	v_mfma_f32_32x32x16_bf16 v[0:15], v[90:93], v[48:51], v[0:15]
	ds_read_b128 v[84:87], v83 offset:32768
	ds_read_b128 v[88:91], v83 offset:49152
	s_waitcnt lgkmcnt(1)
	v_mfma_f32_32x32x16_bf16 v[16:31], v[84:87], v[44:47], v[16:31]
	s_waitcnt lgkmcnt(0)
	v_mfma_f32_32x32x16_bf16 v[0:15], v[88:91], v[44:47], v[0:15]
	ds_read_b128 v[84:87], v82 offset:32768
	ds_read_b128 v[88:91], v82 offset:49152
	s_waitcnt lgkmcnt(1)
	v_mfma_f32_32x32x16_bf16 v[16:31], v[84:87], v[40:43], v[16:31]
	s_waitcnt lgkmcnt(0)
	v_mfma_f32_32x32x16_bf16 v[0:15], v[88:91], v[40:43], v[0:15]
	ds_read_b128 v[82:85], v81 offset:32768
	ds_read_b128 v[86:89], v81 offset:49152
	s_waitcnt lgkmcnt(1)
	v_mfma_f32_32x32x16_bf16 v[16:31], v[82:85], v[36:39], v[16:31]
	s_waitcnt lgkmcnt(0)
	v_mfma_f32_32x32x16_bf16 v[0:15], v[86:89], v[36:39], v[0:15]
	ds_read_b128 v[82:85], v80 offset:32768
	ds_read_b128 v[86:89], v80 offset:49152
	s_waitcnt lgkmcnt(1)
	v_mfma_f32_32x32x16_bf16 v[16:31], v[82:85], v[32:35], v[16:31]
	s_waitcnt lgkmcnt(0)
	v_mfma_f32_32x32x16_bf16 v[0:15], v[86:89], v[32:35], v[0:15]
	s_nop 9
	v_sub_f32_e32 v16, v16, v96
	v_exp_f32_e32 v16, v16
	v_sub_f32_e32 v17, v17, v96
	v_exp_f32_e32 v17, v17
	v_sub_f32_e32 v18, v18, v96
	v_exp_f32_e32 v18, v18
	v_sub_f32_e32 v19, v19, v96
	v_sub_f32_e32 v0, v0, v96
	v_exp_f32_e32 v0, v0
	v_sub_f32_e32 v1, v1, v96
	v_exp_f32_e32 v1, v1
	v_sub_f32_e32 v2, v2, v96
	v_exp_f32_e32 v2, v2
	v_sub_f32_e32 v3, v3, v96
	v_exp_f32_e32 v19, v19
	v_exp_f32_e32 v3, v3
	v_sub_f32_e32 v20, v20, v96
	v_sub_f32_e32 v4, v4, v96
	v_add_f32_e32 v99, v16, v0
	v_exp_f32_e32 v20, v20
	v_exp_f32_e32 v4, v4
	v_sub_f32_e32 v21, v21, v96
	v_sub_f32_e32 v5, v5, v96
	v_add_f32_e32 v100, v17, v1
	v_exp_f32_e32 v21, v21
	v_exp_f32_e32 v5, v5
	v_sub_f32_e32 v22, v22, v96
	v_sub_f32_e32 v6, v6, v96
	v_cvt_pk_bf16_f32 v84, v0, v1
	v_add_f32_e32 v0, v98, v99
	v_add_f32_e32 v101, v18, v2
	v_exp_f32_e32 v22, v22
	v_exp_f32_e32 v6, v6
	v_sub_f32_e32 v23, v23, v96
	v_sub_f32_e32 v7, v7, v96
	v_add_f32_e32 v0, v100, v0
	v_add_f32_e32 v102, v19, v3
	v_exp_f32_e32 v23, v23
	v_exp_f32_e32 v7, v7
	v_sub_f32_e32 v24, v24, v96
	v_sub_f32_e32 v8, v8, v96
	v_add_f32_e32 v0, v101, v0
	v_add_f32_e32 v103, v20, v4
	v_exp_f32_e32 v24, v24
	v_exp_f32_e32 v8, v8
	v_sub_f32_e32 v25, v25, v96
	v_sub_f32_e32 v9, v9, v96
	v_add_f32_e32 v0, v102, v0
	v_add_f32_e32 v104, v21, v5
	v_exp_f32_e32 v25, v25
	v_exp_f32_e32 v9, v9
	v_sub_f32_e32 v26, v26, v96
	v_sub_f32_e32 v10, v10, v96
	v_add_f32_e32 v0, v103, v0
	v_add_f32_e32 v105, v22, v6
	v_exp_f32_e32 v26, v26
	v_exp_f32_e32 v10, v10
	v_sub_f32_e32 v27, v27, v96
	v_sub_f32_e32 v11, v11, v96
	v_add_f32_e32 v0, v104, v0
	v_add_f32_e32 v106, v23, v7
	v_exp_f32_e32 v27, v27
	v_exp_f32_e32 v11, v11
	v_sub_f32_e32 v28, v28, v96
	v_sub_f32_e32 v12, v12, v96
	v_add_f32_e32 v0, v105, v0
	v_add_f32_e32 v107, v24, v8
	v_exp_f32_e32 v28, v28
	v_exp_f32_e32 v12, v12
	v_sub_f32_e32 v29, v29, v96
	v_sub_f32_e32 v13, v13, v96
	v_add_f32_e32 v0, v106, v0
	v_add_f32_e32 v108, v25, v9
	v_exp_f32_e32 v29, v29
	v_exp_f32_e32 v13, v13
	v_sub_f32_e32 v30, v30, v96
	v_sub_f32_e32 v14, v14, v96
	v_add_f32_e32 v0, v107, v0
	v_add_f32_e32 v109, v26, v10
	v_exp_f32_e32 v30, v30
	v_exp_f32_e32 v14, v14
	v_sub_f32_e32 v31, v31, v96
	v_sub_f32_e32 v15, v15, v96
	v_add_f32_e32 v0, v108, v0
	v_add_f32_e32 v110, v27, v11
	v_exp_f32_e32 v31, v31
	v_exp_f32_e32 v15, v15
	v_add_f32_e32 v0, v109, v0
	v_add_f32_e32 v111, v28, v12
	v_add_f32_e32 v0, v110, v0
	v_add_f32_e32 v112, v29, v13
	v_add_f32_e32 v0, v111, v0
	v_add_f32_e32 v113, v30, v14
	v_add_f32_e32 v0, v112, v0
	v_add_f32_e32 v163, v31, v15
	v_add_f32_e32 v0, v113, v0
	v_add_u32_e32 v99, 0x10000, v162
	v_add_u32_e32 v98, 0x14000, v162
	v_cvt_pk_bf16_f32 v86, v4, v5
	v_add_f32_e32 v163, v163, v0
	v_add_u32_e32 v0, v99, v161
	v_add_u32_e32 v4, v98, v161
	v_cvt_pk_bf16_f32 v85, v2, v3
	v_cvt_pk_bf16_f32 v87, v6, v7
	ds_read_b128 v[0:3], v0
	ds_read_b128 v[4:7], v4
	v_add_u32_e32 v100, v99, v160
	v_add_u32_e32 v104, v98, v160
	ds_read_b128 v[100:103], v100
	ds_read_b128 v[104:107], v104
	v_cvt_pk_bf16_f32 v92, v16, v17
	v_cvt_pk_bf16_f32 v93, v18, v19
	v_cvt_pk_bf16_f32 v94, v20, v21
	v_cvt_pk_bf16_f32 v95, v22, v23
	v_cvt_pk_bf16_f32 v88, v24, v25
	v_cvt_pk_bf16_f32 v89, v26, v27
	v_cvt_pk_bf16_f32 v90, v28, v29
	v_cvt_pk_bf16_f32 v91, v30, v31
	v_cvt_pk_bf16_f32 v80, v8, v9
	v_cvt_pk_bf16_f32 v81, v10, v11
	v_cvt_pk_bf16_f32 v82, v12, v13
	v_cvt_pk_bf16_f32 v83, v14, v15
	s_waitcnt lgkmcnt(3)
	v_mfma_f32_32x32x16_bf16 v[16:31], v[0:3], v[142:145], 0
	s_waitcnt lgkmcnt(2)
	v_mfma_f32_32x32x16_bf16 v[0:15], v[4:7], v[142:145], 0
	s_waitcnt lgkmcnt(1)
	v_mfma_f32_32x32x16_bf16 v[16:31], v[100:103], v[138:141], v[16:31]
	v_add_u32_e32 v100, v99, v159
	ds_read_b128 v[100:103], v100
	s_waitcnt lgkmcnt(1)
	v_mfma_f32_32x32x16_bf16 v[0:15], v[104:107], v[138:141], v[0:15]
	v_add_u32_e32 v104, v98, v159
	ds_read_b128 v[104:107], v104
	s_waitcnt lgkmcnt(1)
	v_mfma_f32_32x32x16_bf16 v[16:31], v[100:103], v[134:137], v[16:31]
	v_add_u32_e32 v100, v99, v158
	ds_read_b128 v[100:103], v100
	s_waitcnt lgkmcnt(1)
	v_mfma_f32_32x32x16_bf16 v[0:15], v[104:107], v[134:137], v[0:15]
	v_add_u32_e32 v104, v98, v158
	ds_read_b128 v[104:107], v104
	s_waitcnt lgkmcnt(1)
	v_mfma_f32_32x32x16_bf16 v[16:31], v[100:103], v[130:133], v[16:31]
	v_add_u32_e32 v100, v99, v157
	ds_read_b128 v[100:103], v100
	s_waitcnt lgkmcnt(1)
	v_mfma_f32_32x32x16_bf16 v[0:15], v[104:107], v[130:133], v[0:15]
	v_add_u32_e32 v104, v98, v157
	ds_read_b128 v[104:107], v104
	s_waitcnt lgkmcnt(1)
	v_mfma_f32_32x32x16_bf16 v[16:31], v[100:103], v[126:129], v[16:31]
	v_add_u32_e32 v100, v99, v156
	ds_read_b128 v[100:103], v100
	s_waitcnt lgkmcnt(1)
	v_mfma_f32_32x32x16_bf16 v[0:15], v[104:107], v[126:129], v[0:15]
	v_add_u32_e32 v104, v98, v156
	ds_read_b128 v[104:107], v104
	s_waitcnt lgkmcnt(1)
	v_mfma_f32_32x32x16_bf16 v[16:31], v[100:103], v[122:125], v[16:31]
	v_add_u32_e32 v100, v99, v155
	ds_read_b128 v[100:103], v100
	s_waitcnt lgkmcnt(1)
	v_mfma_f32_32x32x16_bf16 v[0:15], v[104:107], v[122:125], v[0:15]
	v_add_u32_e32 v104, v98, v155
	ds_read_b128 v[104:107], v104
	s_waitcnt lgkmcnt(1)
	v_mfma_f32_32x32x16_bf16 v[16:31], v[100:103], v[118:121], v[16:31]
	v_add_u32_e32 v100, v99, v154
	ds_read_b128 v[100:103], v100
	s_waitcnt lgkmcnt(1)
	v_mfma_f32_32x32x16_bf16 v[0:15], v[104:107], v[118:121], v[0:15]
	v_add_u32_e32 v104, v98, v154
	ds_read_b128 v[104:107], v104
	s_waitcnt lgkmcnt(1)
	v_mfma_f32_32x32x16_bf16 v[16:31], v[100:103], v[114:117], v[16:31]
	v_add_u32_e32 v100, v99, v153
	ds_read_b128 v[100:103], v100
	s_waitcnt lgkmcnt(1)
	v_mfma_f32_32x32x16_bf16 v[0:15], v[104:107], v[114:117], v[0:15]
	v_add_u32_e32 v104, v98, v153
	ds_read_b128 v[104:107], v104
	s_waitcnt lgkmcnt(1)
	v_mfma_f32_32x32x16_bf16 v[16:31], v[100:103], v[60:63], v[16:31]
	v_add_u32_e32 v100, v99, v152
	ds_read_b128 v[100:103], v100
	s_waitcnt lgkmcnt(1)
	v_mfma_f32_32x32x16_bf16 v[0:15], v[104:107], v[60:63], v[0:15]
	v_add_u32_e32 v104, v98, v152
	ds_read_b128 v[104:107], v104
	s_waitcnt lgkmcnt(1)
	v_mfma_f32_32x32x16_bf16 v[16:31], v[100:103], v[56:59], v[16:31]
	v_add_u32_e32 v100, v99, v151
	ds_read_b128 v[100:103], v100
	s_waitcnt lgkmcnt(1)
	v_mfma_f32_32x32x16_bf16 v[0:15], v[104:107], v[56:59], v[0:15]
	v_add_u32_e32 v104, v98, v151
	ds_read_b128 v[104:107], v104
	s_waitcnt lgkmcnt(1)
	v_mfma_f32_32x32x16_bf16 v[16:31], v[100:103], v[52:55], v[16:31]
	v_add_u32_e32 v100, v99, v150
	ds_read_b128 v[100:103], v100
	s_waitcnt lgkmcnt(1)
	v_mfma_f32_32x32x16_bf16 v[0:15], v[104:107], v[52:55], v[0:15]
	v_add_u32_e32 v104, v98, v150
	ds_read_b128 v[104:107], v104
	s_waitcnt lgkmcnt(1)
	v_mfma_f32_32x32x16_bf16 v[16:31], v[100:103], v[48:51], v[16:31]
	v_add_u32_e32 v100, v99, v149
	ds_read_b128 v[100:103], v100
	s_waitcnt lgkmcnt(1)
	v_mfma_f32_32x32x16_bf16 v[0:15], v[104:107], v[48:51], v[0:15]
	v_add_u32_e32 v104, v98, v149
	ds_read_b128 v[104:107], v104
	s_waitcnt lgkmcnt(1)
	v_mfma_f32_32x32x16_bf16 v[16:31], v[100:103], v[44:47], v[16:31]
	v_add_u32_e32 v100, v99, v148
	ds_read_b128 v[100:103], v100
	s_waitcnt lgkmcnt(1)
	v_mfma_f32_32x32x16_bf16 v[0:15], v[104:107], v[44:47], v[0:15]
	v_add_u32_e32 v104, v98, v148
	ds_read_b128 v[104:107], v104
	s_waitcnt lgkmcnt(1)
	v_mfma_f32_32x32x16_bf16 v[16:31], v[100:103], v[40:43], v[16:31]
	v_add_u32_e32 v100, v99, v147
	ds_read_b128 v[100:103], v100
	v_add_u32_e32 v99, v99, v146
	s_waitcnt lgkmcnt(1)
	v_mfma_f32_32x32x16_bf16 v[0:15], v[104:107], v[40:43], v[0:15]
	v_add_u32_e32 v104, v98, v147
	ds_read_b128 v[104:107], v104
	v_add_u32_e32 v98, v98, v146
	s_waitcnt lgkmcnt(1)
	v_mfma_f32_32x32x16_bf16 v[16:31], v[100:103], v[36:39], v[16:31]
	ds_read_b128 v[100:103], v99
	s_waitcnt lgkmcnt(1)
	v_mfma_f32_32x32x16_bf16 v[0:15], v[104:107], v[36:39], v[0:15]
	ds_read_b128 v[104:107], v98
	s_waitcnt lgkmcnt(1)
	v_mfma_f32_32x32x16_bf16 v[16:31], v[100:103], v[32:35], v[16:31]
	s_waitcnt lgkmcnt(0)
	v_mfma_f32_32x32x16_bf16 v[0:15], v[104:107], v[32:35], v[0:15]
	s_nop 9
	v_sub_f32_e32 v16, v16, v96
	v_exp_f32_e32 v16, v16
	v_sub_f32_e32 v17, v17, v96
	v_exp_f32_e32 v17, v17
	v_sub_f32_e32 v18, v18, v96
	v_exp_f32_e32 v18, v18
	v_sub_f32_e32 v19, v19, v96
	v_sub_f32_e32 v0, v0, v96
	v_exp_f32_e32 v0, v0
	v_sub_f32_e32 v1, v1, v96
	v_exp_f32_e32 v1, v1
	v_sub_f32_e32 v2, v2, v96
	v_exp_f32_e32 v2, v2
	v_sub_f32_e32 v3, v3, v96
	v_exp_f32_e32 v19, v19
	v_exp_f32_e32 v3, v3
	v_sub_f32_e32 v20, v20, v96
	v_sub_f32_e32 v4, v4, v96
	v_add_f32_e32 v164, v16, v0
	v_exp_f32_e32 v20, v20
	v_exp_f32_e32 v4, v4
	v_sub_f32_e32 v21, v21, v96
	v_sub_f32_e32 v5, v5, v96
	v_add_f32_e32 v165, v17, v1
	v_exp_f32_e32 v21, v21
	v_exp_f32_e32 v5, v5
	v_sub_f32_e32 v22, v22, v96
	v_sub_f32_e32 v6, v6, v96
	v_cvt_pk_bf16_f32 v102, v0, v1
	v_add_f32_e32 v0, v163, v164
	v_add_f32_e32 v166, v18, v2
	v_exp_f32_e32 v22, v22
	v_exp_f32_e32 v6, v6
	v_sub_f32_e32 v23, v23, v96
	v_sub_f32_e32 v7, v7, v96
	v_add_f32_e32 v0, v165, v0
	v_add_f32_e32 v167, v19, v3
	v_exp_f32_e32 v23, v23
	v_exp_f32_e32 v7, v7
	v_sub_f32_e32 v24, v24, v96
	v_sub_f32_e32 v8, v8, v96
	v_add_f32_e32 v0, v166, v0
	v_add_f32_e32 v168, v20, v4
	v_exp_f32_e32 v24, v24
	v_exp_f32_e32 v8, v8
	v_sub_f32_e32 v25, v25, v96
	v_sub_f32_e32 v9, v9, v96
	v_add_f32_e32 v0, v167, v0
	v_add_f32_e32 v169, v21, v5
	v_exp_f32_e32 v25, v25
	v_exp_f32_e32 v9, v9
	v_sub_f32_e32 v26, v26, v96
	v_sub_f32_e32 v10, v10, v96
	v_add_f32_e32 v0, v168, v0
	v_add_f32_e32 v170, v22, v6
	v_exp_f32_e32 v26, v26
	v_exp_f32_e32 v10, v10
	v_sub_f32_e32 v27, v27, v96
	v_sub_f32_e32 v11, v11, v96
	v_add_f32_e32 v0, v169, v0
	v_add_f32_e32 v171, v23, v7
	v_exp_f32_e32 v27, v27
	v_exp_f32_e32 v11, v11
	v_sub_f32_e32 v28, v28, v96
	v_sub_f32_e32 v12, v12, v96
	v_add_f32_e32 v0, v170, v0
	v_add_f32_e32 v172, v24, v8
	v_exp_f32_e32 v28, v28
	v_exp_f32_e32 v12, v12
	v_sub_f32_e32 v29, v29, v96
	v_sub_f32_e32 v13, v13, v96
	v_add_f32_e32 v0, v171, v0
	v_add_f32_e32 v173, v25, v9
	v_exp_f32_e32 v29, v29
	v_exp_f32_e32 v13, v13
	v_sub_f32_e32 v30, v30, v96
	v_sub_f32_e32 v14, v14, v96
	v_add_f32_e32 v0, v172, v0
	v_add_f32_e32 v174, v26, v10
	v_exp_f32_e32 v30, v30
	v_exp_f32_e32 v14, v14
	v_sub_f32_e32 v31, v31, v96
	v_sub_f32_e32 v15, v15, v96
	v_add_f32_e32 v0, v173, v0
	v_add_f32_e32 v175, v27, v11
	v_exp_f32_e32 v31, v31
	v_exp_f32_e32 v15, v15
	v_add_f32_e32 v0, v174, v0
	v_add_f32_e32 v176, v28, v12
	v_add_f32_e32 v0, v175, v0
	v_add_f32_e32 v177, v29, v13
	v_add_f32_e32 v0, v176, v0
	v_add_f32_e32 v178, v30, v14
	v_add_f32_e32 v0, v177, v0
	v_add_f32_e32 v179, v31, v15
	v_add_f32_e32 v0, v178, v0
	v_add_u32_e32 v164, 0x18000, v162
	v_add_u32_e32 v162, 0x1c000, v162
	v_cvt_pk_bf16_f32 v104, v4, v5
	v_add_f32_e32 v163, v179, v0
	v_add_u32_e32 v0, v164, v161
	v_add_u32_e32 v4, v162, v161
	v_cvt_pk_bf16_f32 v103, v2, v3
	v_cvt_pk_bf16_f32 v105, v6, v7
	ds_read_b128 v[0:3], v0
	ds_read_b128 v[4:7], v4
	v_cvt_pk_bf16_f32 v110, v16, v17
	v_cvt_pk_bf16_f32 v111, v18, v19
	v_cvt_pk_bf16_f32 v112, v20, v21
	v_cvt_pk_bf16_f32 v113, v22, v23
	v_cvt_pk_bf16_f32 v106, v24, v25
	v_cvt_pk_bf16_f32 v107, v26, v27
	v_cvt_pk_bf16_f32 v108, v28, v29
	v_cvt_pk_bf16_f32 v109, v30, v31
	v_cvt_pk_bf16_f32 v98, v8, v9
	v_cvt_pk_bf16_f32 v99, v10, v11
	v_cvt_pk_bf16_f32 v100, v12, v13
	v_cvt_pk_bf16_f32 v101, v14, v15
	s_waitcnt lgkmcnt(1)
	v_mfma_f32_32x32x16_bf16 v[16:31], v[0:3], v[142:145], 0
	s_waitcnt lgkmcnt(0)
	v_mfma_f32_32x32x16_bf16 v[0:15], v[4:7], v[142:145], 0
	v_add_u32_e32 v142, v164, v160
	v_add_u32_e32 v160, v162, v160
	ds_read_b128 v[142:145], v142
	ds_read_b128 v[166:169], v160
	s_waitcnt lgkmcnt(1)
	v_mfma_f32_32x32x16_bf16 v[16:31], v[142:145], v[138:141], v[16:31]
	v_add_u32_e32 v142, v162, v159
	ds_read_b128 v[142:145], v142
	s_waitcnt lgkmcnt(1)
	v_mfma_f32_32x32x16_bf16 v[0:15], v[166:169], v[138:141], v[0:15]
	v_add_u32_e32 v138, v164, v159
	ds_read_b128 v[138:141], v138
	s_waitcnt lgkmcnt(0)
	v_mfma_f32_32x32x16_bf16 v[16:31], v[138:141], v[134:137], v[16:31]
	v_add_u32_e32 v138, v162, v158
	ds_read_b128 v[138:141], v138
	v_mfma_f32_32x32x16_bf16 v[0:15], v[142:145], v[134:137], v[0:15]
	v_add_u32_e32 v134, v164, v158
	ds_read_b128 v[134:137], v134
	s_waitcnt lgkmcnt(0)
	v_mfma_f32_32x32x16_bf16 v[16:31], v[134:137], v[130:133], v[16:31]
	v_add_u32_e32 v134, v162, v157
	ds_read_b128 v[134:137], v134
	v_mfma_f32_32x32x16_bf16 v[0:15], v[138:141], v[130:133], v[0:15]
	v_add_u32_e32 v130, v164, v157
	ds_read_b128 v[130:133], v130
	s_waitcnt lgkmcnt(0)
	v_mfma_f32_32x32x16_bf16 v[16:31], v[130:133], v[126:129], v[16:31]
	v_add_u32_e32 v130, v162, v156
	ds_read_b128 v[130:133], v130
	v_mfma_f32_32x32x16_bf16 v[0:15], v[134:137], v[126:129], v[0:15]
	v_add_u32_e32 v126, v164, v156
	ds_read_b128 v[126:129], v126
	v_mov_b32_e32 v134, v245
	s_waitcnt lgkmcnt(0)
	v_mfma_f32_32x32x16_bf16 v[16:31], v[126:129], v[122:125], v[16:31]
	v_add_u32_e32 v126, v162, v155
	ds_read_b128 v[126:129], v126
	v_mfma_f32_32x32x16_bf16 v[0:15], v[130:133], v[122:125], v[0:15]
	v_add_u32_e32 v122, v164, v155
	ds_read_b128 v[122:125], v122
	s_waitcnt lgkmcnt(0)
	v_mfma_f32_32x32x16_bf16 v[16:31], v[122:125], v[118:121], v[16:31]
	v_add_u32_e32 v122, v162, v154
	ds_read_b128 v[122:125], v122
	v_mfma_f32_32x32x16_bf16 v[0:15], v[126:129], v[118:121], v[0:15]
	v_add_u32_e32 v118, v164, v154
	ds_read_b128 v[118:121], v118
	s_waitcnt lgkmcnt(0)
	v_mfma_f32_32x32x16_bf16 v[16:31], v[118:121], v[114:117], v[16:31]
	v_add_u32_e32 v118, v162, v153
	ds_read_b128 v[118:121], v118
	v_mfma_f32_32x32x16_bf16 v[0:15], v[122:125], v[114:117], v[0:15]
	v_add_u32_e32 v114, v164, v153
	ds_read_b128 v[114:117], v114
	s_waitcnt lgkmcnt(0)
	v_mfma_f32_32x32x16_bf16 v[16:31], v[114:117], v[60:63], v[16:31]
	v_add_u32_e32 v114, v162, v152
	ds_read_b128 v[114:117], v114
	v_mfma_f32_32x32x16_bf16 v[0:15], v[118:121], v[60:63], v[0:15]
	v_add_u32_e32 v60, v164, v152
	ds_read_b128 v[60:63], v60
	s_waitcnt lgkmcnt(0)
	v_mfma_f32_32x32x16_bf16 v[16:31], v[60:63], v[56:59], v[16:31]
	v_add_u32_e32 v60, v162, v151
	ds_read_b128 v[60:63], v60
	v_mfma_f32_32x32x16_bf16 v[0:15], v[114:117], v[56:59], v[0:15]
	v_add_u32_e32 v56, v164, v151
	ds_read_b128 v[56:59], v56
	s_waitcnt lgkmcnt(0)
	v_mfma_f32_32x32x16_bf16 v[16:31], v[56:59], v[52:55], v[16:31]
	v_add_u32_e32 v56, v162, v150
	ds_read_b128 v[56:59], v56
	v_mfma_f32_32x32x16_bf16 v[0:15], v[60:63], v[52:55], v[0:15]
	v_add_u32_e32 v52, v164, v150
	ds_read_b128 v[52:55], v52
	s_waitcnt lgkmcnt(0)
	v_mfma_f32_32x32x16_bf16 v[16:31], v[52:55], v[48:51], v[16:31]
	v_add_u32_e32 v52, v162, v149
	ds_read_b128 v[52:55], v52
	v_mfma_f32_32x32x16_bf16 v[0:15], v[56:59], v[48:51], v[0:15]
	v_add_u32_e32 v48, v164, v149
	ds_read_b128 v[48:51], v48
	s_waitcnt lgkmcnt(0)
	v_mfma_f32_32x32x16_bf16 v[16:31], v[48:51], v[44:47], v[16:31]
	v_add_u32_e32 v48, v162, v148
	ds_read_b128 v[48:51], v48
	v_mfma_f32_32x32x16_bf16 v[0:15], v[52:55], v[44:47], v[0:15]
	v_add_u32_e32 v44, v164, v148
	ds_read_b128 v[44:47], v44
	s_waitcnt lgkmcnt(0)
	v_mfma_f32_32x32x16_bf16 v[16:31], v[44:47], v[40:43], v[16:31]
	v_add_u32_e32 v44, v162, v147
	ds_read_b128 v[44:47], v44
	v_mfma_f32_32x32x16_bf16 v[0:15], v[48:51], v[40:43], v[0:15]
	v_add_u32_e32 v40, v164, v147
	ds_read_b128 v[40:43], v40
	s_waitcnt lgkmcnt(0)
	v_mfma_f32_32x32x16_bf16 v[16:31], v[40:43], v[36:39], v[16:31]
	v_add_u32_e32 v40, v162, v146
	ds_read_b128 v[40:43], v40
	v_mfma_f32_32x32x16_bf16 v[0:15], v[44:47], v[36:39], v[0:15]
	v_add_u32_e32 v36, v164, v146
	ds_read_b128 v[36:39], v36
	s_waitcnt lgkmcnt(0)
	s_barrier
	v_mfma_f32_32x32x16_bf16 v[0:15], v[40:43], v[32:35], v[0:15]
	v_mfma_f32_32x32x16_bf16 v[16:31], v[36:39], v[32:35], v[16:31]
	s_nop 10
	v_sub_f32_e32 v0, v0, v96
	v_exp_f32_e32 v33, v0
	v_sub_f32_e32 v10, v10, v96
	v_sub_f32_e32 v12, v12, v96
	v_sub_f32_e32 v14, v14, v96
	v_sub_f32_e32 v0, v17, v96
	v_exp_f32_e32 v35, v0
	v_sub_f32_e32 v0, v1, v96
	v_exp_f32_e32 v36, v0
	v_sub_f32_e32 v0, v18, v96
	v_exp_f32_e32 v38, v0
	v_sub_f32_e32 v0, v2, v96
	v_exp_f32_e32 v39, v0
	v_sub_f32_e32 v0, v19, v96
	v_exp_f32_e32 v41, v0
	v_sub_f32_e32 v0, v3, v96
	v_exp_f32_e32 v42, v0
	v_sub_f32_e32 v0, v20, v96
	v_exp_f32_e32 v44, v0
	v_sub_f32_e32 v0, v4, v96
	v_exp_f32_e32 v45, v0
	v_sub_f32_e32 v0, v21, v96
	v_exp_f32_e32 v47, v0
	v_sub_f32_e32 v0, v5, v96
	v_exp_f32_e32 v48, v0
	v_sub_f32_e32 v0, v22, v96
	v_exp_f32_e32 v1, v0
	v_sub_f32_e32 v0, v6, v96
	v_exp_f32_e32 v3, v0
	v_sub_f32_e32 v0, v23, v96
	v_sub_f32_e32 v2, v7, v96
	v_sub_f32_e32 v6, v24, v96
	v_exp_f32_e32 v0, v0
	v_exp_f32_e32 v2, v2
	v_exp_f32_e32 v7, v6
	v_sub_f32_e32 v6, v8, v96
	v_exp_f32_e32 v17, v6
	v_sub_f32_e32 v6, v25, v96
	v_exp_f32_e32 v6, v6
	v_sub_f32_e32 v18, v26, v96
	v_exp_f32_e32 v21, v10
	v_sub_f32_e32 v10, v27, v96
	v_exp_f32_e32 v19, v18
	v_exp_f32_e32 v18, v10
	v_sub_f32_e32 v22, v28, v96
	v_exp_f32_e32 v25, v12
	v_sub_f32_e32 v12, v29, v96
	v_pk_add_f32 v[4:5], v[0:1], v[2:3]
	v_exp_f32_e32 v23, v22
	v_exp_f32_e32 v22, v12
	v_sub_f32_e32 v26, v30, v96
	v_exp_f32_e32 v29, v14
	v_sub_f32_e32 v14, v31, v96
	v_pk_mov_b32 v[0:1], v[0:1], v[0:1] op_sel:[1,0]
	v_sub_f32_e32 v16, v16, v96
	v_sub_f32_e32 v8, v9, v96
	v_exp_f32_e32 v27, v26
	v_exp_f32_e32 v26, v14
	v_cvt_pk_bf16_f32 v129, v0, v1
	v_pk_mov_b32 v[0:1], v[2:3], v[2:3] op_sel:[1,0]
	v_exp_f32_e32 v32, v16
	v_exp_f32_e32 v16, v8
	v_sub_f32_e32 v10, v11, v96
	v_cvt_pk_bf16_f32 v121, v0, v1
	v_pk_mov_b32 v[0:1], v[6:7], v[6:7] op_sel:[1,0]
	v_exp_f32_e32 v20, v10
	v_sub_f32_e32 v12, v13, v96
	v_cvt_pk_bf16_f32 v122, v0, v1
	v_pk_mov_b32 v[0:1], v[18:19], v[18:19] op_sel:[1,0]
	v_exp_f32_e32 v24, v12
	v_sub_f32_e32 v14, v15, v96
	v_cvt_pk_bf16_f32 v123, v0, v1
	v_pk_mov_b32 v[0:1], v[22:23], v[22:23] op_sel:[1,0]
	v_exp_f32_e32 v28, v14
	v_cvt_pk_bf16_f32 v124, v0, v1
	v_pk_mov_b32 v[0:1], v[26:27], v[26:27] op_sel:[1,0]
	v_add_f32_e32 v34, v32, v33
	v_cvt_pk_bf16_f32 v125, v0, v1
	v_pk_mov_b32 v[0:1], v[16:17], v[16:17] op_sel:[1,0]
	v_add_f32_e32 v37, v35, v36
	v_cvt_pk_bf16_f32 v114, v0, v1
	v_pk_mov_b32 v[0:1], v[20:21], v[20:21] op_sel:[1,0]
	v_add_f32_e32 v40, v38, v39
	v_cvt_pk_bf16_f32 v115, v0, v1
	v_pk_mov_b32 v[0:1], v[24:25], v[24:25] op_sel:[1,0]
	v_add_f32_e32 v43, v41, v42
	v_cvt_pk_bf16_f32 v116, v0, v1
	v_pk_mov_b32 v[0:1], v[28:29], v[28:29] op_sel:[1,0]
	v_add_f32_e32 v46, v44, v45
	v_cvt_pk_bf16_f32 v117, v0, v1
	v_add_f32_e32 v0, v163, v34
	v_add_f32_e32 v0, v37, v0
	v_add_f32_e32 v0, v40, v0
	v_add_f32_e32 v0, v43, v0
	v_add_f32_e32 v49, v47, v48
	v_add_f32_e32 v0, v46, v0
	v_add_f32_e32 v0, v49, v0
	v_add_f32_e32 v0, v5, v0
	v_pk_add_f32 v[8:9], v[6:7], v[16:17]
	v_add_f32_e32 v0, v4, v0
	v_add_f32_e32 v0, v9, v0
	v_pk_add_f32 v[10:11], v[18:19], v[20:21]
	v_add_f32_e32 v0, v8, v0
	v_add_f32_e32 v0, v11, v0
	v_pk_add_f32 v[12:13], v[22:23], v[24:25]
	v_add_f32_e32 v0, v10, v0
	v_add_f32_e32 v0, v13, v0
	v_pk_add_f32 v[14:15], v[26:27], v[28:29]
	v_add_f32_e32 v0, v12, v0
	v_add_f32_e32 v0, v15, v0
	v_add_f32_e32 v1, v14, v0
	v_cndmask_b32_e32 v0, v227, v234, vcc
	v_lshlrev_b32_e32 v0, 2, v0
	v_ashrrev_i32_e32 v5, 6, v134
	ds_bpermute_b32 v4, v0, v1
	v_lshlrev_b32_e32 v0, 5, v5
	v_bfe_u32 v10, v134, 5, 1
	v_or_b32_e32 v2, v0, v10
	v_ashrrev_i32_e32 v3, 31, v2
	v_and_b32_e32 v11, 31, v134
	v_lshlrev_b64 v[6:7], 12, v[2:3]
	v_and_b32_e32 v3, 32, v134
	v_lshlrev_b32_e32 v3, 1, v3
	v_lshlrev_b32_e32 v8, 4, v11
	v_lshl_add_u64 v[6:7], s[36:37], 0, v[6:7]
	v_xor_b32_e32 v96, v8, v3
	v_readfirstlane_b32 s7, v5
	v_lshl_add_u64 v[6:7], v[6:7], 0, v[96:97]
	v_lshl_add_u64 v[6:7], v[6:7], 0, s[20:21]
	s_lshl_b32 s7, s7, 14
	s_add_i32 s8, s7, 0
	s_mov_b32 s9, m0
	s_mov_b32 m0, s8
	s_nop 0
	global_load_lds_dwordx4 v[6:7], off
	s_mov_b32 m0, s9
	v_or_b32_e32 v6, 2, v2
	v_ashrrev_i32_e32 v7, 31, v6
	v_lshlrev_b32_e32 v3, 2, v6
	v_lshlrev_b64 v[8:9], 12, v[6:7]
	v_bitop3_b32 v3, v3, v11, 12 bitop3:0x6c
	v_lshl_add_u64 v[8:9], s[36:37], 0, v[8:9]
	v_lshlrev_b32_e32 v6, 4, v3
	v_mov_b32_e32 v7, v97
	v_lshl_add_u64 v[6:7], v[8:9], 0, v[6:7]
	v_lshl_add_u64 v[6:7], v[6:7], 0, s[20:21]
	s_add_i32 s5, s7, s5
	s_mov_b32 s8, m0
	s_mov_b32 m0, s5
	s_nop 0
	global_load_lds_dwordx4 v[6:7], off
	s_mov_b32 m0, s8
	v_or_b32_e32 v6, 4, v2
	v_ashrrev_i32_e32 v7, 31, v6
	v_lshlrev_b64 v[6:7], 12, v[6:7]
	v_lshl_add_u64 v[6:7], s[36:37], 0, v[6:7]
	v_lshl_add_u64 v[6:7], v[6:7], 0, v[96:97]
	v_lshl_add_u64 v[6:7], v[6:7], 0, s[20:21]
	s_add_i32 s5, s7, s6
	s_mov_b32 s6, m0
	s_mov_b32 m0, s5
	s_nop 0
	global_load_lds_dwordx4 v[6:7], off
	s_mov_b32 m0, s6
	v_or_b32_e32 v6, 6, v2
	v_ashrrev_i32_e32 v7, 31, v6
	v_lshlrev_b32_e32 v3, 2, v6
	v_lshlrev_b64 v[8:9], 12, v[6:7]
	v_bitop3_b32 v3, v3, v11, 12 bitop3:0x6c
	v_lshl_add_u64 v[8:9], s[36:37], 0, v[8:9]
	v_lshlrev_b32_e32 v6, 4, v3
	v_mov_b32_e32 v7, v97
	v_lshl_add_u64 v[6:7], v[8:9], 0, v[6:7]
	v_lshl_add_u64 v[6:7], v[6:7], 0, s[20:21]
	s_add_i32 s5, s7, s18
	s_mov_b32 s6, m0
	s_mov_b32 m0, s5
	s_nop 0
	global_load_lds_dwordx4 v[6:7], off
	s_mov_b32 m0, s6
	v_or_b32_e32 v6, 8, v2
	v_ashrrev_i32_e32 v7, 31, v6
	v_lshlrev_b64 v[6:7], 12, v[6:7]
	v_lshl_add_u64 v[6:7], s[36:37], 0, v[6:7]
	v_lshl_add_u64 v[6:7], v[6:7], 0, v[96:97]
	v_lshl_add_u64 v[6:7], v[6:7], 0, s[20:21]
	s_add_i32 s4, s7, s4
	s_mov_b32 s5, m0
	s_mov_b32 m0, s4
	s_nop 0
	global_load_lds_dwordx4 v[6:7], off
	s_mov_b32 m0, s5
	v_or_b32_e32 v6, 10, v2
	v_ashrrev_i32_e32 v7, 31, v6
	v_lshlrev_b32_e32 v3, 2, v6
	v_lshlrev_b64 v[8:9], 12, v[6:7]
	v_bitop3_b32 v3, v3, v11, 12 bitop3:0x6c
	v_lshl_add_u64 v[8:9], s[36:37], 0, v[8:9]
	v_lshlrev_b32_e32 v6, 4, v3
	v_mov_b32_e32 v7, v97
	v_lshl_add_u64 v[6:7], v[8:9], 0, v[6:7]
	v_lshl_add_u64 v[6:7], v[6:7], 0, s[20:21]
	s_add_i32 s4, s7, s19
	s_mov_b32 s5, m0
	s_mov_b32 m0, s4
	s_nop 0
	global_load_lds_dwordx4 v[6:7], off
	s_mov_b32 m0, s5
	v_or_b32_e32 v6, 12, v2
	v_ashrrev_i32_e32 v7, 31, v6
	v_lshlrev_b64 v[6:7], 12, v[6:7]
	v_lshl_add_u64 v[6:7], s[36:37], 0, v[6:7]
	v_lshl_add_u64 v[6:7], v[6:7], 0, v[96:97]
	v_lshl_add_u64 v[6:7], v[6:7], 0, s[20:21]
	s_add_i32 s4, s7, s41
	s_mov_b32 s5, m0
	s_mov_b32 m0, s4
	s_nop 0
	global_load_lds_dwordx4 v[6:7], off
	s_mov_b32 m0, s5
	v_or_b32_e32 v6, 14, v2
	v_ashrrev_i32_e32 v7, 31, v6
	v_lshlrev_b32_e32 v3, 2, v6
	v_lshlrev_b64 v[8:9], 12, v[6:7]
	v_bitop3_b32 v3, v3, v11, 12 bitop3:0x6c
	v_lshl_add_u64 v[8:9], s[36:37], 0, v[8:9]
	v_lshlrev_b32_e32 v6, 4, v3
	v_mov_b32_e32 v7, v97
	v_lshl_add_u64 v[6:7], v[8:9], 0, v[6:7]
	v_lshl_add_u64 v[6:7], v[6:7], 0, s[20:21]
	s_add_i32 s4, s7, s42
	s_mov_b32 s5, m0
	s_mov_b32 m0, s4
	s_nop 0
	global_load_lds_dwordx4 v[6:7], off
	s_mov_b32 m0, s5
	v_or_b32_e32 v6, 16, v2
	v_ashrrev_i32_e32 v7, 31, v6
	v_lshlrev_b64 v[6:7], 12, v[6:7]
	v_lshl_add_u64 v[6:7], s[36:37], 0, v[6:7]
	v_lshl_add_u64 v[6:7], v[6:7], 0, v[96:97]
	v_lshl_add_u64 v[6:7], v[6:7], 0, s[20:21]
	s_add_i32 s4, s7, s43
	s_mov_b32 s5, m0
	s_mov_b32 m0, s4
	s_nop 0
	global_load_lds_dwordx4 v[6:7], off
	s_mov_b32 m0, s5
	v_or_b32_e32 v6, 18, v2
	v_ashrrev_i32_e32 v7, 31, v6
	v_lshlrev_b32_e32 v3, 2, v6
	v_lshlrev_b64 v[8:9], 12, v[6:7]
	v_bitop3_b32 v3, v3, v11, 12 bitop3:0x6c
	v_lshl_add_u64 v[8:9], s[36:37], 0, v[8:9]
	v_lshlrev_b32_e32 v6, 4, v3
	v_mov_b32_e32 v7, v97
	v_lshl_add_u64 v[6:7], v[8:9], 0, v[6:7]
	v_lshl_add_u64 v[6:7], v[6:7], 0, s[20:21]
	s_add_i32 s4, s7, s44
	s_mov_b32 s5, m0
	s_mov_b32 m0, s4
	s_nop 0
	global_load_lds_dwordx4 v[6:7], off
	s_mov_b32 m0, s5
	v_or_b32_e32 v6, 20, v2
	v_ashrrev_i32_e32 v7, 31, v6
	v_lshlrev_b64 v[6:7], 12, v[6:7]
	v_lshl_add_u64 v[6:7], s[36:37], 0, v[6:7]
	v_lshl_add_u64 v[6:7], v[6:7], 0, v[96:97]
	v_lshl_add_u64 v[6:7], v[6:7], 0, s[20:21]
	s_add_i32 s4, s7, s45
	s_mov_b32 s5, m0
	s_mov_b32 m0, s4
	s_nop 0
	global_load_lds_dwordx4 v[6:7], off
	s_mov_b32 m0, s5
	v_or_b32_e32 v6, 22, v2
	v_ashrrev_i32_e32 v7, 31, v6
	v_lshlrev_b32_e32 v3, 2, v6
	v_lshlrev_b64 v[8:9], 12, v[6:7]
	v_bitop3_b32 v3, v3, v11, 12 bitop3:0x6c
	v_lshl_add_u64 v[8:9], s[36:37], 0, v[8:9]
	v_lshlrev_b32_e32 v6, 4, v3
	v_mov_b32_e32 v7, v97
	v_lshl_add_u64 v[6:7], v[8:9], 0, v[6:7]
	v_lshl_add_u64 v[6:7], v[6:7], 0, s[20:21]
	s_add_i32 s4, s7, s46
	s_mov_b32 s5, m0
	s_mov_b32 m0, s4
	s_nop 0
	global_load_lds_dwordx4 v[6:7], off
	s_mov_b32 m0, s5
	v_or_b32_e32 v6, 24, v2
	v_ashrrev_i32_e32 v7, 31, v6
	v_lshlrev_b64 v[6:7], 12, v[6:7]
	v_lshl_add_u64 v[6:7], s[36:37], 0, v[6:7]
	v_lshl_add_u64 v[6:7], v[6:7], 0, v[96:97]
	v_lshl_add_u64 v[6:7], v[6:7], 0, s[20:21]
	s_add_i32 s4, s7, s47
	s_mov_b32 s5, m0
	s_mov_b32 m0, s4
	s_nop 0
	global_load_lds_dwordx4 v[6:7], off
	s_mov_b32 m0, s5
	v_or_b32_e32 v6, 26, v2
	v_ashrrev_i32_e32 v7, 31, v6
	v_lshlrev_b32_e32 v3, 2, v6
	v_lshlrev_b64 v[8:9], 12, v[6:7]
	v_bitop3_b32 v3, v3, v11, 12 bitop3:0x6c
	v_lshl_add_u64 v[8:9], s[36:37], 0, v[8:9]
	v_lshlrev_b32_e32 v6, 4, v3
	v_mov_b32_e32 v7, v97
	v_lshl_add_u64 v[6:7], v[8:9], 0, v[6:7]
	v_lshl_add_u64 v[6:7], v[6:7], 0, s[20:21]
	s_add_i32 s4, s7, s48
	s_mov_b32 s5, m0
	s_mov_b32 m0, s4
	s_nop 0
	global_load_lds_dwordx4 v[6:7], off
	s_mov_b32 m0, s5
	v_or_b32_e32 v6, 28, v2
	v_ashrrev_i32_e32 v7, 31, v6
	v_lshlrev_b64 v[6:7], 12, v[6:7]
	v_lshl_add_u64 v[6:7], s[36:37], 0, v[6:7]
	v_lshl_add_u64 v[6:7], v[6:7], 0, v[96:97]
	v_or_b32_e32 v2, 30, v2
	v_lshl_add_u64 v[6:7], v[6:7], 0, s[20:21]
	v_ashrrev_i32_e32 v3, 31, v2
	s_add_i32 s4, s7, s49
	s_mov_b32 s5, m0
	s_mov_b32 m0, s4
	s_nop 0
	global_load_lds_dwordx4 v[6:7], off
	s_mov_b32 m0, s5
	v_lshlrev_b64 v[6:7], 12, v[2:3]
	v_lshlrev_b32_e32 v2, 2, v2
	v_bitop3_b32 v2, v2, v11, 12 bitop3:0x6c
	v_lshl_add_u64 v[6:7], s[36:37], 0, v[6:7]
	v_lshlrev_b32_e32 v96, 4, v2
	v_lshl_add_u64 v[2:3], v[6:7], 0, v[96:97]
	v_lshl_add_u64 v[2:3], v[2:3], 0, s[20:21]
	s_waitcnt lgkmcnt(0)
	v_add_f32_e32 v1, v1, v4
	s_add_i32 s7, s7, s50
	s_mov_b32 s4, m0
	s_mov_b32 m0, s7
	s_nop 0
	global_load_lds_dwordx4 v[2:3], off
	s_mov_b32 m0, s4
	s_waitcnt vmcnt(0)
	s_nop 0
	v_div_scale_f32 v2, s[4:5], v1, v1, 1.0
	v_rcp_f32_e32 v3, v2
	s_barrier
	v_cvt_pk_bf16_f32 v120, v45, v48
	v_fma_f32 v4, -v2, v3, 1.0
	v_fmac_f32_e32 v3, v4, v3
	v_div_scale_f32 v4, vcc, 1.0, v1, 1.0
	v_mul_f32_e32 v6, v4, v3
	v_fma_f32 v7, -v2, v6, v4
	v_fmac_f32_e32 v6, v7, v3
	v_fma_f32 v2, -v2, v6, v4
	v_div_fmas_f32 v2, v2, v3, v6
	v_div_fixup_f32 v130, v2, v1, 1.0
	v_ashrrev_i32_e32 v1, 31, v0
	v_lshl_add_u64 v[0:1], s[38:39], 0, v[0:1]
	v_lshlrev_b32_e32 v3, 3, v134
	v_lshlrev_b64 v[0:1], 11, v[0:1]
	v_and_b32_e32 v3, 24, v3
	v_lshl_add_u64 v[0:1], s[26:27], 0, v[0:1]
	v_lshl_add_u64 v[0:1], v[0:1], 0, s[28:29]
	v_lshlrev_b32_e32 v96, 1, v3
	v_bfe_u32 v2, v134, 2, 2
	v_lshl_add_u64 v[132:133], v[0:1], 0, v[96:97]
	v_lshlrev_b32_e32 v0, 1, v134
	v_lshlrev_b32_e32 v136, 6, v2
	v_add_u32_e32 v4, 0, v3
	v_and_b32_e32 v137, 32, v0
	v_lshlrev_b32_e32 v0, 11, v10
	v_lshlrev_b32_e32 v1, 9, v2
	v_or_b32_e32 v139, v136, v137
	v_add3_u32 v138, v4, v0, v1
	v_add_u32_e32 v131, v138, v139
	ds_read_b64_tr_b16 v[0:1], v131
	ds_read_b64_tr_b16 v[2:3], v131 offset:4096
	v_bitop3_b32 v158, v137, v136, 64 bitop3:0x36
	v_add_u32_e32 v143, v138, v158
	s_waitcnt lgkmcnt(0)
	v_mfma_f32_32x32x16_bf16 v[48:63], v[0:3], v[76:79], 0
	ds_read_b64_tr_b16 v[0:1], v143
	ds_read_b64_tr_b16 v[2:3], v143 offset:4096
	v_bitop3_b32 v148, v137, v136, s16 bitop3:0x36
	v_add_u32_e32 v142, v138, v148
	v_cvt_pk_bf16_f32 v126, v32, v35
	v_cvt_pk_bf16_f32 v127, v38, v41
	v_cvt_pk_bf16_f32 v128, v44, v47
	v_cvt_pk_bf16_f32 v118, v33, v36
	v_cvt_pk_bf16_f32 v119, v39, v42
	s_waitcnt lgkmcnt(0)
	v_mfma_f32_32x32x16_bf16 v[32:47], v[0:3], v[76:79], 0
	ds_read_b64_tr_b16 v[0:1], v142
	ds_read_b64_tr_b16 v[2:3], v142 offset:4096
	v_bitop3_b32 v96, v137, v136, s17 bitop3:0x36
	v_add_u32_e32 v141, v138, v96
	v_lshl_add_u32 v140, v5, 11, s51
	v_lshlrev_b32_e32 v5, 6, v134
	v_and_b32_e32 v5, 0x7c0, v5
	v_lshlrev_b32_e32 v6, 3, v10
	s_waitcnt lgkmcnt(0)
	v_mfma_f32_32x32x16_bf16 v[16:31], v[0:3], v[76:79], 0
	ds_read_b64_tr_b16 v[0:1], v141
	ds_read_b64_tr_b16 v[2:3], v141 offset:4096
	ds_read_b64_tr_b16 v[144:145], v131 offset:8192
	ds_read_b64_tr_b16 v[146:147], v131 offset:12288
	v_add3_u32 v135, v140, v5, v6
	v_add_u32_e32 v149, 0x16000, v138
	s_movk_i32 s4, 0x140
	s_add_u32 s0, s0, s94
	s_addc_u32 s1, s1, s70
	s_waitcnt lgkmcnt(0)
	v_mfma_f32_32x32x16_bf16 v[48:63], v[144:147], v[72:75], v[48:63]
	ds_read_b64_tr_b16 v[144:145], v143 offset:8192
	ds_read_b64_tr_b16 v[146:147], v143 offset:12288
	s_mov_b64 s[28:29], 0
	s_waitcnt lgkmcnt(0)
	v_mfma_f32_32x32x16_bf16 v[32:47], v[144:147], v[72:75], v[32:47]
	ds_read_b64_tr_b16 v[144:145], v142 offset:8192
	ds_read_b64_tr_b16 v[146:147], v142 offset:12288
	v_mfma_f32_32x32x16_bf16 v[0:15], v[0:3], v[76:79], 0
	s_waitcnt lgkmcnt(0)
	v_mfma_f32_32x32x16_bf16 v[16:31], v[144:147], v[72:75], v[16:31]
	ds_read_b64_tr_b16 v[144:145], v141 offset:8192
	ds_read_b64_tr_b16 v[146:147], v141 offset:12288
	s_waitcnt lgkmcnt(0)
	v_mfma_f32_32x32x16_bf16 v[0:15], v[144:147], v[72:75], v[0:15]
	ds_read_b64_tr_b16 v[144:145], v131 offset:16384
	ds_read_b64_tr_b16 v[146:147], v131 offset:20480
	s_waitcnt lgkmcnt(0)
	v_mfma_f32_32x32x16_bf16 v[48:63], v[144:147], v[68:71], v[48:63]
	ds_read_b64_tr_b16 v[144:145], v143 offset:16384
	ds_read_b64_tr_b16 v[146:147], v143 offset:20480
	s_waitcnt lgkmcnt(0)
	v_mfma_f32_32x32x16_bf16 v[32:47], v[144:147], v[68:71], v[32:47]
	ds_read_b64_tr_b16 v[144:145], v142 offset:16384
	ds_read_b64_tr_b16 v[146:147], v142 offset:20480
	s_waitcnt lgkmcnt(0)
	v_mfma_f32_32x32x16_bf16 v[16:31], v[144:147], v[68:71], v[16:31]
	ds_read_b64_tr_b16 v[144:145], v141 offset:16384
	ds_read_b64_tr_b16 v[146:147], v141 offset:20480
	s_waitcnt lgkmcnt(0)
	v_mfma_f32_32x32x16_bf16 v[0:15], v[144:147], v[68:71], v[0:15]
	ds_read_b64_tr_b16 v[144:145], v131 offset:24576
	ds_read_b64_tr_b16 v[146:147], v131 offset:28672
	s_waitcnt lgkmcnt(0)
	v_mfma_f32_32x32x16_bf16 v[48:63], v[144:147], v[64:67], v[48:63]
	ds_read_b64_tr_b16 v[144:145], v143 offset:24576
	ds_read_b64_tr_b16 v[146:147], v143 offset:28672
	s_waitcnt lgkmcnt(0)
	v_mfma_f32_32x32x16_bf16 v[32:47], v[144:147], v[64:67], v[32:47]
	ds_read_b64_tr_b16 v[144:145], v142 offset:24576
	ds_read_b64_tr_b16 v[146:147], v142 offset:28672
	s_waitcnt lgkmcnt(0)
	v_mfma_f32_32x32x16_bf16 v[16:31], v[144:147], v[64:67], v[16:31]
	ds_read_b64_tr_b16 v[144:145], v141 offset:24576
	ds_read_b64_tr_b16 v[146:147], v141 offset:28672
	s_waitcnt lgkmcnt(0)
	v_mfma_f32_32x32x16_bf16 v[0:15], v[144:147], v[64:67], v[0:15]
	ds_read_b64_tr_b16 v[144:145], v131 offset:32768
	ds_read_b64_tr_b16 v[146:147], v131 offset:36864
	s_waitcnt lgkmcnt(0)
	v_mfma_f32_32x32x16_bf16 v[48:63], v[144:147], v[92:95], v[48:63]
	ds_read_b64_tr_b16 v[144:145], v143 offset:32768
	ds_read_b64_tr_b16 v[146:147], v143 offset:36864
	s_waitcnt lgkmcnt(0)
	v_mfma_f32_32x32x16_bf16 v[32:47], v[144:147], v[92:95], v[32:47]
	ds_read_b64_tr_b16 v[144:145], v142 offset:32768
	ds_read_b64_tr_b16 v[146:147], v142 offset:36864
	s_waitcnt lgkmcnt(0)
	v_mfma_f32_32x32x16_bf16 v[16:31], v[144:147], v[92:95], v[16:31]
	ds_read_b64_tr_b16 v[144:145], v141 offset:32768
	ds_read_b64_tr_b16 v[146:147], v141 offset:36864
	s_waitcnt lgkmcnt(0)
	v_mfma_f32_32x32x16_bf16 v[0:15], v[144:147], v[92:95], v[0:15]
	ds_read_b64_tr_b16 v[144:145], v131 offset:40960
	ds_read_b64_tr_b16 v[146:147], v131 offset:45056
	s_waitcnt lgkmcnt(0)
	v_mfma_f32_32x32x16_bf16 v[48:63], v[144:147], v[88:91], v[48:63]
	ds_read_b64_tr_b16 v[144:145], v143 offset:40960
	ds_read_b64_tr_b16 v[146:147], v143 offset:45056
	s_waitcnt lgkmcnt(0)
	v_mfma_f32_32x32x16_bf16 v[32:47], v[144:147], v[88:91], v[32:47]
	ds_read_b64_tr_b16 v[144:145], v142 offset:40960
	ds_read_b64_tr_b16 v[146:147], v142 offset:45056
	s_waitcnt lgkmcnt(0)
	v_mfma_f32_32x32x16_bf16 v[16:31], v[144:147], v[88:91], v[16:31]
	ds_read_b64_tr_b16 v[144:145], v141 offset:40960
	ds_read_b64_tr_b16 v[146:147], v141 offset:45056
	s_waitcnt lgkmcnt(0)
	v_mfma_f32_32x32x16_bf16 v[0:15], v[144:147], v[88:91], v[0:15]
	ds_read_b64_tr_b16 v[144:145], v131 offset:49152
	ds_read_b64_tr_b16 v[146:147], v131 offset:53248
	s_waitcnt lgkmcnt(0)
	v_mfma_f32_32x32x16_bf16 v[48:63], v[144:147], v[84:87], v[48:63]
	ds_read_b64_tr_b16 v[144:145], v143 offset:49152
	ds_read_b64_tr_b16 v[146:147], v143 offset:53248
	s_waitcnt lgkmcnt(0)
	v_mfma_f32_32x32x16_bf16 v[32:47], v[144:147], v[84:87], v[32:47]
	ds_read_b64_tr_b16 v[144:145], v142 offset:49152
	ds_read_b64_tr_b16 v[146:147], v142 offset:53248
	s_waitcnt lgkmcnt(0)
	v_mfma_f32_32x32x16_bf16 v[16:31], v[144:147], v[84:87], v[16:31]
	ds_read_b64_tr_b16 v[144:145], v141 offset:49152
	ds_read_b64_tr_b16 v[146:147], v141 offset:53248
	s_waitcnt lgkmcnt(0)
	v_mfma_f32_32x32x16_bf16 v[0:15], v[144:147], v[84:87], v[0:15]
	ds_read_b64_tr_b16 v[144:145], v131 offset:57344
	ds_read_b64_tr_b16 v[146:147], v131 offset:61440
	s_waitcnt lgkmcnt(0)
	v_mfma_f32_32x32x16_bf16 v[48:63], v[144:147], v[80:83], v[48:63]
	ds_read_b64_tr_b16 v[144:145], v143 offset:57344
	ds_read_b64_tr_b16 v[146:147], v143 offset:61440
	s_waitcnt lgkmcnt(0)
	v_mfma_f32_32x32x16_bf16 v[32:47], v[144:147], v[80:83], v[32:47]
	ds_read_b64_tr_b16 v[144:145], v142 offset:57344
	ds_read_b64_tr_b16 v[146:147], v142 offset:61440
	s_waitcnt lgkmcnt(0)
	v_mfma_f32_32x32x16_bf16 v[16:31], v[144:147], v[80:83], v[16:31]
	ds_read_b64_tr_b16 v[142:143], v141 offset:57344
	ds_read_b64_tr_b16 v[144:145], v141 offset:61440
	v_add_u32_e32 v141, 0x11000, v138
	s_waitcnt lgkmcnt(0)
	v_mfma_f32_32x32x16_bf16 v[0:15], v[142:145], v[80:83], v[0:15]
	v_add_u32_e32 v142, 0x10000, v138
	v_add_u32_e32 v143, v142, v139
	ds_read_b64_tr_b16 v[144:145], v143
	v_add_u32_e32 v143, v141, v139
	ds_read_b64_tr_b16 v[146:147], v143
	v_add_u32_e32 v143, v142, v158
	s_waitcnt lgkmcnt(0)
	v_mfma_f32_32x32x16_bf16 v[48:63], v[144:147], v[110:113], v[48:63]
	ds_read_b64_tr_b16 v[144:145], v143
	v_add_u32_e32 v143, v141, v158
	ds_read_b64_tr_b16 v[146:147], v143
	v_add_u32_e32 v143, v142, v148
	s_waitcnt lgkmcnt(0)
	v_mfma_f32_32x32x16_bf16 v[32:47], v[144:147], v[110:113], v[32:47]
	ds_read_b64_tr_b16 v[144:145], v143
	v_add_u32_e32 v143, v141, v148
	ds_read_b64_tr_b16 v[146:147], v143
	v_add_u32_e32 v143, v142, v96
	s_waitcnt lgkmcnt(0)
	v_mfma_f32_32x32x16_bf16 v[16:31], v[144:147], v[110:113], v[16:31]
	ds_read_b64_tr_b16 v[144:145], v143
	v_add_u32_e32 v143, v141, v96
	ds_read_b64_tr_b16 v[146:147], v143
	v_add_u32_e32 v143, 0x13000, v138
	s_waitcnt lgkmcnt(0)
	v_mfma_f32_32x32x16_bf16 v[0:15], v[144:147], v[110:113], v[0:15]
	v_add_u32_e32 v144, 0x12000, v138
	v_add_u32_e32 v145, v144, v139
	ds_read_b64_tr_b16 v[150:151], v145
	v_add_u32_e32 v145, v143, v139
	ds_read_b64_tr_b16 v[152:153], v145
	v_add_u32_e32 v145, v144, v158
	v_add_u32_e32 v146, 0x14000, v138
	s_waitcnt lgkmcnt(0)
	v_mfma_f32_32x32x16_bf16 v[48:63], v[150:153], v[106:109], v[48:63]
	ds_read_b64_tr_b16 v[150:151], v145
	v_add_u32_e32 v145, v143, v158
	ds_read_b64_tr_b16 v[152:153], v145
	v_add_u32_e32 v145, v144, v148
	v_add_u32_e32 v147, v146, v139
	s_waitcnt lgkmcnt(0)
	v_mfma_f32_32x32x16_bf16 v[32:47], v[150:153], v[106:109], v[32:47]
	ds_read_b64_tr_b16 v[150:151], v145
	v_add_u32_e32 v145, v143, v148
	ds_read_b64_tr_b16 v[152:153], v145
	v_add_u32_e32 v145, v144, v96
	s_waitcnt lgkmcnt(0)
	v_mfma_f32_32x32x16_bf16 v[16:31], v[150:153], v[106:109], v[16:31]
	ds_read_b64_tr_b16 v[150:151], v145
	v_add_u32_e32 v145, v143, v96
	ds_read_b64_tr_b16 v[152:153], v145
	v_add_u32_e32 v145, 0x15000, v138
	s_waitcnt lgkmcnt(0)
	v_mfma_f32_32x32x16_bf16 v[0:15], v[150:153], v[106:109], v[0:15]
	ds_read_b64_tr_b16 v[150:151], v147
	v_add_u32_e32 v147, v145, v139
	ds_read_b64_tr_b16 v[152:153], v147
	v_add_u32_e32 v147, v146, v158
	s_waitcnt lgkmcnt(0)
	v_mfma_f32_32x32x16_bf16 v[48:63], v[150:153], v[102:105], v[48:63]
	ds_read_b64_tr_b16 v[150:151], v147
	v_add_u32_e32 v147, v145, v158
	ds_read_b64_tr_b16 v[152:153], v147
	v_add_u32_e32 v147, v146, v148
	s_waitcnt lgkmcnt(0)
	v_mfma_f32_32x32x16_bf16 v[32:47], v[150:153], v[102:105], v[32:47]
	ds_read_b64_tr_b16 v[150:151], v147
	v_add_u32_e32 v147, v145, v148
	ds_read_b64_tr_b16 v[152:153], v147
	v_add_u32_e32 v147, v146, v96
	s_waitcnt lgkmcnt(0)
	v_mfma_f32_32x32x16_bf16 v[16:31], v[150:153], v[102:105], v[16:31]
	ds_read_b64_tr_b16 v[150:151], v147
	v_add_u32_e32 v147, v145, v96
	ds_read_b64_tr_b16 v[152:153], v147
	v_add_u32_e32 v147, 0x17000, v138
	s_waitcnt lgkmcnt(0)
	v_mfma_f32_32x32x16_bf16 v[0:15], v[150:153], v[102:105], v[0:15]
	v_add_u32_e32 v150, v149, v139
	v_add_u32_e32 v152, v147, v139
	ds_read_b64_tr_b16 v[150:151], v150
	ds_read_b64_tr_b16 v[152:153], v152
	s_waitcnt lgkmcnt(0)
	v_mfma_f32_32x32x16_bf16 v[48:63], v[150:153], v[98:101], v[48:63]
	v_add_u32_e32 v150, v149, v158
	v_add_u32_e32 v152, v147, v158
	ds_read_b64_tr_b16 v[150:151], v150
	ds_read_b64_tr_b16 v[152:153], v152
	s_waitcnt lgkmcnt(0)
	v_mfma_f32_32x32x16_bf16 v[32:47], v[150:153], v[98:101], v[32:47]
	v_add_u32_e32 v150, v149, v148
	v_add_u32_e32 v152, v147, v148
	ds_read_b64_tr_b16 v[150:151], v150
	ds_read_b64_tr_b16 v[152:153], v152
	s_waitcnt lgkmcnt(0)
	v_mfma_f32_32x32x16_bf16 v[16:31], v[150:153], v[98:101], v[16:31]
	v_add_u32_e32 v150, v149, v96
	v_add_u32_e32 v152, v147, v96
	ds_read_b64_tr_b16 v[150:151], v150
	ds_read_b64_tr_b16 v[152:153], v152
	s_waitcnt lgkmcnt(0)
	v_mfma_f32_32x32x16_bf16 v[0:15], v[150:153], v[98:101], v[0:15]
	v_add_u32_e32 v151, 0x18000, v138
	v_add_u32_e32 v150, 0x19000, v138
	v_add_u32_e32 v152, v151, v139
	v_add_u32_e32 v154, v150, v139
	ds_read_b64_tr_b16 v[152:153], v152
	ds_read_b64_tr_b16 v[154:155], v154
	s_waitcnt lgkmcnt(0)
	v_mfma_f32_32x32x16_bf16 v[48:63], v[152:155], v[126:129], v[48:63]
	v_add_u32_e32 v152, v151, v158
	v_add_u32_e32 v154, v150, v158
	ds_read_b64_tr_b16 v[152:153], v152
	ds_read_b64_tr_b16 v[154:155], v154
	s_waitcnt lgkmcnt(0)
	v_mfma_f32_32x32x16_bf16 v[32:47], v[152:155], v[126:129], v[32:47]
	v_add_u32_e32 v152, v151, v148
	v_add_u32_e32 v154, v150, v148
	ds_read_b64_tr_b16 v[152:153], v152
	ds_read_b64_tr_b16 v[154:155], v154
	s_waitcnt lgkmcnt(0)
	v_mfma_f32_32x32x16_bf16 v[16:31], v[152:155], v[126:129], v[16:31]
	v_add_u32_e32 v152, v151, v96
	v_add_u32_e32 v154, v150, v96
	ds_read_b64_tr_b16 v[152:153], v152
	ds_read_b64_tr_b16 v[154:155], v154
	s_waitcnt lgkmcnt(0)
	v_mfma_f32_32x32x16_bf16 v[0:15], v[152:155], v[126:129], v[0:15]
	v_add_u32_e32 v153, 0x1a000, v138
	v_add_u32_e32 v152, 0x1b000, v138
	v_add_u32_e32 v154, v153, v139
	v_add_u32_e32 v156, v152, v139
	ds_read_b64_tr_b16 v[154:155], v154
	ds_read_b64_tr_b16 v[156:157], v156
	s_waitcnt lgkmcnt(0)
	v_mfma_f32_32x32x16_bf16 v[48:63], v[154:157], v[122:125], v[48:63]
	v_add_u32_e32 v154, v153, v158
	v_add_u32_e32 v156, v152, v158
	ds_read_b64_tr_b16 v[154:155], v154
	ds_read_b64_tr_b16 v[156:157], v156
	s_waitcnt lgkmcnt(0)
	v_mfma_f32_32x32x16_bf16 v[32:47], v[154:157], v[122:125], v[32:47]
	v_add_u32_e32 v154, v153, v148
	v_add_u32_e32 v156, v152, v148
	ds_read_b64_tr_b16 v[154:155], v154
	ds_read_b64_tr_b16 v[156:157], v156
	s_waitcnt lgkmcnt(0)
	v_mfma_f32_32x32x16_bf16 v[16:31], v[154:157], v[122:125], v[16:31]
	v_add_u32_e32 v154, v153, v96
	v_add_u32_e32 v156, v152, v96
	ds_read_b64_tr_b16 v[154:155], v154
	ds_read_b64_tr_b16 v[156:157], v156
	s_waitcnt lgkmcnt(0)
	v_mfma_f32_32x32x16_bf16 v[0:15], v[154:157], v[122:125], v[0:15]
	v_add_u32_e32 v155, 0x1c000, v138
	v_add_u32_e32 v154, 0x1d000, v138
	v_add_u32_e32 v156, v155, v139
	ds_read_b64_tr_b16 v[160:161], v156
	v_add_u32_e32 v156, v154, v139
	ds_read_b64_tr_b16 v[162:163], v156
	v_add_u32_e32 v156, v155, v158
	s_waitcnt lgkmcnt(0)
	v_mfma_f32_32x32x16_bf16 v[48:63], v[160:163], v[118:121], v[48:63]
	ds_read_b64_tr_b16 v[160:161], v156
	v_add_u32_e32 v156, v154, v158
	ds_read_b64_tr_b16 v[162:163], v156
	v_add_u32_e32 v156, v155, v148
	v_add_u32_e32 v157, 0x1e000, v138
	v_add_u32_e32 v159, v157, v139
	s_waitcnt lgkmcnt(0)
	v_mfma_f32_32x32x16_bf16 v[32:47], v[160:163], v[118:121], v[32:47]
	ds_read_b64_tr_b16 v[160:161], v156
	v_add_u32_e32 v156, v154, v148
	ds_read_b64_tr_b16 v[162:163], v156
	v_add_u32_e32 v156, v155, v96
	s_waitcnt lgkmcnt(0)
	v_mfma_f32_32x32x16_bf16 v[16:31], v[160:163], v[118:121], v[16:31]
	ds_read_b64_tr_b16 v[160:161], v156
	v_add_u32_e32 v156, v154, v96
	ds_read_b64_tr_b16 v[162:163], v156
	v_add_u32_e32 v156, 0x1f000, v138
	s_waitcnt lgkmcnt(0)
	v_mfma_f32_32x32x16_bf16 v[0:15], v[160:163], v[118:121], v[0:15]
	ds_read_b64_tr_b16 v[160:161], v159
	v_add_u32_e32 v159, v156, v139
	ds_read_b64_tr_b16 v[162:163], v159
	v_add_u32_e32 v159, v157, v158
	v_add_u32_e32 v158, v156, v158
	s_waitcnt lgkmcnt(0)
	v_mfma_f32_32x32x16_bf16 v[48:63], v[160:163], v[114:117], v[48:63]
	ds_read_b64_tr_b16 v[160:161], v159
	ds_read_b64_tr_b16 v[162:163], v158
	v_add_u32_e32 v158, v157, v148
	v_add_u32_e32 v148, v156, v148
	ds_read_b64_tr_b16 v[158:159], v158
	s_nop 6
	v_pk_mul_f32 v[48:49], v[130:131], v[48:49] op_sel_hi:[0,1]
	s_waitcnt lgkmcnt(1)
	v_mfma_f32_32x32x16_bf16 v[32:47], v[160:163], v[114:117], v[32:47]
	ds_read_b64_tr_b16 v[160:161], v148
	v_add_u32_e32 v148, v157, v96
	v_add_u32_e32 v96, v156, v96
	v_bfe_u32 v162, v134, 2, 4
	v_mul_f32_e64 v50, v130, v50
	v_mul_f32_e64 v51, v130, v51
	v_cvt_pk_bf16_f32 v48, v48, v49
	v_cvt_pk_bf16_f32 v49, v50, v51
	s_waitcnt lgkmcnt(0)
	v_mfma_f32_32x32x16_bf16 v[16:31], v[158:161], v[114:117], v[16:31]
	ds_read_b64_tr_b16 v[158:159], v148
	ds_read_b64_tr_b16 v[160:161], v96
	v_xor_b32_e32 v148, v162, v134
	v_lshlrev_b32_e32 v148, 4, v148
	v_lshlrev_b32_e32 v96, 6, v162
	v_and_b32_e32 v163, 48, v148
	v_lshlrev_b32_e32 v50, 4, v134
	v_add3_u32 v148, v140, v96, v163
	v_and_b32_e32 v96, 48, v50
	s_waitcnt lgkmcnt(0)
	v_mfma_f32_32x32x16_bf16 v[0:15], v[158:161], v[114:117], v[0:15]
	v_add_u32_e32 v158, v135, v96
	ds_write_b64 v158, v[48:49]
	v_mul_f32_e64 v48, v130, v52
	v_mul_f32_e64 v49, v130, v53
	v_mul_f32_e64 v50, v130, v54
	v_mul_f32_e64 v51, v130, v55
	v_cvt_pk_bf16_f32 v48, v48, v49
	v_cvt_pk_bf16_f32 v49, v50, v51
	v_xad_u32 v159, v96, 16, v135
	ds_write_b64 v159, v[48:49]
	v_pk_mul_f32 v[48:49], v[130:131], v[56:57] op_sel_hi:[0,1]
	v_pk_mul_f32 v[50:51], v[130:131], v[58:59] op_sel_hi:[0,1]
	v_cvt_pk_bf16_f32 v48, v48, v49
	v_cvt_pk_bf16_f32 v49, v50, v51
	v_xad_u32 v160, v96, 32, v135
	ds_write_b64 v160, v[48:49]
	v_pk_mul_f32 v[48:49], v[130:131], v[60:61] op_sel_hi:[0,1]
	v_pk_mul_f32 v[50:51], v[130:131], v[62:63] op_sel_hi:[0,1]
	v_cvt_pk_bf16_f32 v48, v48, v49
	v_cvt_pk_bf16_f32 v49, v50, v51
	v_xad_u32 v161, v96, 48, v135
	ds_write_b64 v161, v[48:49]
	ds_read_b128 v[48:51], v148
	v_lshlrev_b32_e32 v96, 11, v162
	v_lshl_add_u64 v[134:135], v[132:133], 0, v[96:97]
	v_or_b32_e32 v52, 16, v162
	v_pk_mul_f32 v[32:33], v[130:131], v[32:33] op_sel_hi:[0,1]
	s_waitcnt lgkmcnt(0)
	global_store_dwordx4 v[134:135], v[48:51], off sc1
	v_pk_mul_f32 v[34:35], v[130:131], v[34:35] op_sel_hi:[0,1]
	v_cvt_pk_bf16_f32 v32, v32, v33
	v_lshlrev_b32_e32 v48, 6, v52
	v_add3_u32 v140, v140, v48, v163
	v_cvt_pk_bf16_f32 v33, v34, v35
	ds_read_b128 v[48:51], v140
	ds_write_b64 v158, v[32:33]
	v_pk_mul_f32 v[32:33], v[130:131], v[36:37] op_sel_hi:[0,1]
	v_pk_mul_f32 v[34:35], v[130:131], v[38:39] op_sel_hi:[0,1]
	v_cvt_pk_bf16_f32 v32, v32, v33
	v_cvt_pk_bf16_f32 v33, v34, v35
	ds_write_b64 v159, v[32:33]
	v_pk_mul_f32 v[32:33], v[130:131], v[40:41] op_sel_hi:[0,1]
	v_pk_mul_f32 v[34:35], v[130:131], v[42:43] op_sel_hi:[0,1]
	v_cvt_pk_bf16_f32 v32, v32, v33
	v_cvt_pk_bf16_f32 v33, v34, v35
	ds_write_b64 v160, v[32:33]
	v_pk_mul_f32 v[32:33], v[130:131], v[44:45] op_sel_hi:[0,1]
	v_pk_mul_f32 v[34:35], v[130:131], v[46:47] op_sel_hi:[0,1]
	v_cvt_pk_bf16_f32 v32, v32, v33
	v_cvt_pk_bf16_f32 v33, v34, v35
	ds_write_b64 v161, v[32:33]
	ds_read_b128 v[32:35], v148
	v_pk_mul_f32 v[16:17], v[130:131], v[16:17] op_sel_hi:[0,1]
	v_pk_mul_f32 v[18:19], v[130:131], v[18:19] op_sel_hi:[0,1]
	v_cvt_pk_bf16_f32 v16, v16, v17
	v_cvt_pk_bf16_f32 v17, v18, v19
	s_waitcnt lgkmcnt(0)
	global_store_dwordx4 v[134:135], v[32:35], off offset:64 sc1
	ds_read_b128 v[32:35], v140
	ds_write_b64 v158, v[16:17]
	v_pk_mul_f32 v[16:17], v[130:131], v[20:21] op_sel_hi:[0,1]
	v_pk_mul_f32 v[18:19], v[130:131], v[22:23] op_sel_hi:[0,1]
	v_cvt_pk_bf16_f32 v16, v16, v17
	v_cvt_pk_bf16_f32 v17, v18, v19
	ds_write_b64 v159, v[16:17]
	v_pk_mul_f32 v[16:17], v[130:131], v[24:25] op_sel_hi:[0,1]
	v_pk_mul_f32 v[18:19], v[130:131], v[26:27] op_sel_hi:[0,1]
	v_cvt_pk_bf16_f32 v16, v16, v17
	v_cvt_pk_bf16_f32 v17, v18, v19
	ds_write_b64 v160, v[16:17]
	v_pk_mul_f32 v[16:17], v[130:131], v[28:29] op_sel_hi:[0,1]
	v_pk_mul_f32 v[18:19], v[130:131], v[30:31] op_sel_hi:[0,1]
	v_cvt_pk_bf16_f32 v16, v16, v17
	v_cvt_pk_bf16_f32 v17, v18, v19
	ds_write_b64 v161, v[16:17]
	ds_read_b128 v[16:19], v148
	v_pk_mul_f32 v[0:1], v[130:131], v[0:1] op_sel_hi:[0,1]
	v_pk_mul_f32 v[2:3], v[130:131], v[2:3] op_sel_hi:[0,1]
	v_cvt_pk_bf16_f32 v0, v0, v1
	v_cvt_pk_bf16_f32 v1, v2, v3
	s_waitcnt lgkmcnt(0)
	global_store_dwordx4 v[134:135], v[16:19], off offset:128 sc1
	ds_read_b128 v[16:19], v140
	ds_write_b64 v158, v[0:1]
	v_pk_mul_f32 v[0:1], v[130:131], v[4:5] op_sel_hi:[0,1]
	v_pk_mul_f32 v[2:3], v[130:131], v[6:7] op_sel_hi:[0,1]
	v_cvt_pk_bf16_f32 v0, v0, v1
	v_cvt_pk_bf16_f32 v1, v2, v3
	ds_write_b64 v159, v[0:1]
	v_pk_mul_f32 v[0:1], v[130:131], v[8:9] op_sel_hi:[0,1]
	v_pk_mul_f32 v[2:3], v[130:131], v[10:11] op_sel_hi:[0,1]
	v_cvt_pk_bf16_f32 v0, v0, v1
	v_cvt_pk_bf16_f32 v1, v2, v3
	ds_write_b64 v160, v[0:1]
	v_pk_mul_f32 v[0:1], v[130:131], v[12:13] op_sel_hi:[0,1]
	v_pk_mul_f32 v[2:3], v[130:131], v[14:15] op_sel_hi:[0,1]
	v_cvt_pk_bf16_f32 v0, v0, v1
	v_cvt_pk_bf16_f32 v1, v2, v3
	ds_write_b64 v161, v[0:1]
	ds_read_b128 v[0:3], v148
	v_lshlrev_b32_e32 v96, 11, v52
	v_lshl_add_u64 v[132:133], v[132:133], 0, v[96:97]
	global_store_dwordx4 v[132:133], v[48:51], off sc1
	global_store_dwordx4 v[132:133], v[32:35], off offset:64 sc1
	s_waitcnt lgkmcnt(0)
	global_store_dwordx4 v[134:135], v[0:3], off offset:192 sc1
	ds_read_b128 v[0:3], v140
	global_store_dwordx4 v[132:133], v[16:19], off offset:128 sc1
	v_bitop3_b32 v163, v137, v136, s4 bitop3:0x36
	v_add_u32_e32 v165, v138, v163
	s_movk_i32 s4, 0x180
	s_waitcnt lgkmcnt(0)
	global_store_dwordx4 v[132:133], v[0:3], off offset:192 sc1
	ds_read_b64_tr_b16 v[0:1], v131 offset:256
	ds_read_b64_tr_b16 v[2:3], v131 offset:4352
	s_waitcnt lgkmcnt(0)
	v_mfma_f32_32x32x16_bf16 v[48:63], v[0:3], v[76:79], 0
	ds_read_b64_tr_b16 v[0:1], v165
	ds_read_b64_tr_b16 v[2:3], v165 offset:4096
	v_or_b32_e32 v162, 0x100, v139
	v_bitop3_b32 v139, v137, v136, s4 bitop3:0x36
	v_add_u32_e32 v164, v138, v139
	s_movk_i32 s4, 0x1c0
	v_bitop3_b32 v96, v137, v136, s4 bitop3:0x36
	v_add_u32_e32 v136, v138, v96
	s_waitcnt lgkmcnt(0)
	v_mfma_f32_32x32x16_bf16 v[32:47], v[0:3], v[76:79], 0
	ds_read_b64_tr_b16 v[0:1], v164
	ds_read_b64_tr_b16 v[2:3], v164 offset:4096
	s_waitcnt lgkmcnt(0)
	v_mfma_f32_32x32x16_bf16 v[16:31], v[0:3], v[76:79], 0
	ds_read_b64_tr_b16 v[0:1], v136
	ds_read_b64_tr_b16 v[2:3], v136 offset:4096
	s_waitcnt lgkmcnt(0)
	v_mfma_f32_32x32x16_bf16 v[0:15], v[0:3], v[76:79], 0
	ds_read_b64_tr_b16 v[76:77], v131 offset:8448
	ds_read_b64_tr_b16 v[78:79], v131 offset:12544
	s_waitcnt lgkmcnt(0)
	v_mfma_f32_32x32x16_bf16 v[48:63], v[76:79], v[72:75], v[48:63]
	ds_read_b64_tr_b16 v[76:77], v165 offset:8192
	ds_read_b64_tr_b16 v[78:79], v165 offset:12288
	s_waitcnt lgkmcnt(0)
	v_mfma_f32_32x32x16_bf16 v[32:47], v[76:79], v[72:75], v[32:47]
	ds_read_b64_tr_b16 v[76:77], v164 offset:8192
	ds_read_b64_tr_b16 v[78:79], v164 offset:12288
	s_waitcnt lgkmcnt(0)
	v_mfma_f32_32x32x16_bf16 v[16:31], v[76:79], v[72:75], v[16:31]
	ds_read_b64_tr_b16 v[76:77], v136 offset:8192
	ds_read_b64_tr_b16 v[78:79], v136 offset:12288
	s_waitcnt lgkmcnt(0)
	v_mfma_f32_32x32x16_bf16 v[0:15], v[76:79], v[72:75], v[0:15]
	ds_read_b64_tr_b16 v[72:73], v131 offset:16640
	ds_read_b64_tr_b16 v[74:75], v131 offset:20736
	s_waitcnt lgkmcnt(0)
	v_mfma_f32_32x32x16_bf16 v[48:63], v[72:75], v[68:71], v[48:63]
	ds_read_b64_tr_b16 v[72:73], v165 offset:16384
	ds_read_b64_tr_b16 v[74:75], v165 offset:20480
	s_waitcnt lgkmcnt(0)
	v_mfma_f32_32x32x16_bf16 v[32:47], v[72:75], v[68:71], v[32:47]
	ds_read_b64_tr_b16 v[72:73], v164 offset:16384
	ds_read_b64_tr_b16 v[74:75], v164 offset:20480
	s_waitcnt lgkmcnt(0)
	v_mfma_f32_32x32x16_bf16 v[16:31], v[72:75], v[68:71], v[16:31]
	ds_read_b64_tr_b16 v[72:73], v136 offset:16384
	ds_read_b64_tr_b16 v[74:75], v136 offset:20480
	s_waitcnt lgkmcnt(0)
	v_mfma_f32_32x32x16_bf16 v[0:15], v[72:75], v[68:71], v[0:15]
	ds_read_b64_tr_b16 v[68:69], v131 offset:24832
	ds_read_b64_tr_b16 v[70:71], v131 offset:28928
	s_waitcnt lgkmcnt(0)
	v_mfma_f32_32x32x16_bf16 v[48:63], v[68:71], v[64:67], v[48:63]
	ds_read_b64_tr_b16 v[68:69], v165 offset:24576
	ds_read_b64_tr_b16 v[70:71], v165 offset:28672
	s_waitcnt lgkmcnt(0)
	v_mfma_f32_32x32x16_bf16 v[32:47], v[68:71], v[64:67], v[32:47]
	ds_read_b64_tr_b16 v[68:69], v164 offset:24576
	ds_read_b64_tr_b16 v[70:71], v164 offset:28672
	s_waitcnt lgkmcnt(0)
	v_mfma_f32_32x32x16_bf16 v[16:31], v[68:71], v[64:67], v[16:31]
	ds_read_b64_tr_b16 v[68:69], v136 offset:24576
	ds_read_b64_tr_b16 v[70:71], v136 offset:28672
	s_waitcnt lgkmcnt(0)
	v_mfma_f32_32x32x16_bf16 v[0:15], v[68:71], v[64:67], v[0:15]
	ds_read_b64_tr_b16 v[64:65], v131 offset:33024
	ds_read_b64_tr_b16 v[66:67], v131 offset:37120
	s_waitcnt lgkmcnt(0)
	v_mfma_f32_32x32x16_bf16 v[48:63], v[64:67], v[92:95], v[48:63]
	ds_read_b64_tr_b16 v[64:65], v165 offset:32768
	ds_read_b64_tr_b16 v[66:67], v165 offset:36864
	s_waitcnt lgkmcnt(0)
	v_mfma_f32_32x32x16_bf16 v[32:47], v[64:67], v[92:95], v[32:47]
	ds_read_b64_tr_b16 v[64:65], v164 offset:32768
	ds_read_b64_tr_b16 v[66:67], v164 offset:36864
	s_waitcnt lgkmcnt(0)
	v_mfma_f32_32x32x16_bf16 v[16:31], v[64:67], v[92:95], v[16:31]
	ds_read_b64_tr_b16 v[64:65], v136 offset:32768
	ds_read_b64_tr_b16 v[66:67], v136 offset:36864
	s_waitcnt lgkmcnt(0)
	v_mfma_f32_32x32x16_bf16 v[0:15], v[64:67], v[92:95], v[0:15]
	ds_read_b64_tr_b16 v[64:65], v131 offset:41216
	ds_read_b64_tr_b16 v[66:67], v131 offset:45312
	s_waitcnt lgkmcnt(0)
	v_mfma_f32_32x32x16_bf16 v[48:63], v[64:67], v[88:91], v[48:63]
	ds_read_b64_tr_b16 v[64:65], v165 offset:40960
	ds_read_b64_tr_b16 v[66:67], v165 offset:45056
	s_waitcnt lgkmcnt(0)
	v_mfma_f32_32x32x16_bf16 v[32:47], v[64:67], v[88:91], v[32:47]
	ds_read_b64_tr_b16 v[64:65], v164 offset:40960
	ds_read_b64_tr_b16 v[66:67], v164 offset:45056
	s_waitcnt lgkmcnt(0)
	v_mfma_f32_32x32x16_bf16 v[16:31], v[64:67], v[88:91], v[16:31]
	ds_read_b64_tr_b16 v[64:65], v136 offset:40960
	ds_read_b64_tr_b16 v[66:67], v136 offset:45056
	s_waitcnt lgkmcnt(0)
	v_mfma_f32_32x32x16_bf16 v[0:15], v[64:67], v[88:91], v[0:15]
	ds_read_b64_tr_b16 v[64:65], v131 offset:49408
	ds_read_b64_tr_b16 v[66:67], v131 offset:53504
	s_waitcnt lgkmcnt(0)
	v_mfma_f32_32x32x16_bf16 v[48:63], v[64:67], v[84:87], v[48:63]
	ds_read_b64_tr_b16 v[64:65], v165 offset:49152
	ds_read_b64_tr_b16 v[66:67], v165 offset:53248
	s_waitcnt lgkmcnt(0)
	v_mfma_f32_32x32x16_bf16 v[32:47], v[64:67], v[84:87], v[32:47]
	ds_read_b64_tr_b16 v[64:65], v164 offset:49152
	ds_read_b64_tr_b16 v[66:67], v164 offset:53248
	s_waitcnt lgkmcnt(0)
	v_mfma_f32_32x32x16_bf16 v[16:31], v[64:67], v[84:87], v[16:31]
	ds_read_b64_tr_b16 v[64:65], v136 offset:49152
	ds_read_b64_tr_b16 v[66:67], v136 offset:53248
	s_waitcnt lgkmcnt(0)
	v_mfma_f32_32x32x16_bf16 v[0:15], v[64:67], v[84:87], v[0:15]
	ds_read_b64_tr_b16 v[64:65], v131 offset:57600
	ds_read_b64_tr_b16 v[66:67], v131 offset:61696
	s_waitcnt lgkmcnt(0)
	v_mfma_f32_32x32x16_bf16 v[48:63], v[64:67], v[80:83], v[48:63]
	ds_read_b64_tr_b16 v[64:65], v165 offset:57344
	ds_read_b64_tr_b16 v[66:67], v165 offset:61440
	s_waitcnt lgkmcnt(0)
	v_mfma_f32_32x32x16_bf16 v[32:47], v[64:67], v[80:83], v[32:47]
	ds_read_b64_tr_b16 v[64:65], v164 offset:57344
	ds_read_b64_tr_b16 v[66:67], v164 offset:61440
	s_waitcnt lgkmcnt(0)
	v_mfma_f32_32x32x16_bf16 v[16:31], v[64:67], v[80:83], v[16:31]
	ds_read_b64_tr_b16 v[64:65], v136 offset:57344
	ds_read_b64_tr_b16 v[66:67], v136 offset:61440
	s_waitcnt lgkmcnt(0)
	v_mfma_f32_32x32x16_bf16 v[0:15], v[64:67], v[80:83], v[0:15]
	v_add_u32_e32 v64, v142, v162
	v_add_u32_e32 v66, v141, v162
	ds_read_b64_tr_b16 v[64:65], v64
	ds_read_b64_tr_b16 v[66:67], v66
	s_waitcnt lgkmcnt(0)
	v_mfma_f32_32x32x16_bf16 v[48:63], v[64:67], v[110:113], v[48:63]
	v_add_u32_e32 v64, v142, v163
	v_add_u32_e32 v66, v141, v163
	ds_read_b64_tr_b16 v[64:65], v64
	ds_read_b64_tr_b16 v[66:67], v66
	s_waitcnt lgkmcnt(0)
	v_mfma_f32_32x32x16_bf16 v[32:47], v[64:67], v[110:113], v[32:47]
	v_add_u32_e32 v64, v142, v139
	v_add_u32_e32 v66, v141, v139
	ds_read_b64_tr_b16 v[64:65], v64
	ds_read_b64_tr_b16 v[66:67], v66
	s_waitcnt lgkmcnt(0)
	v_mfma_f32_32x32x16_bf16 v[16:31], v[64:67], v[110:113], v[16:31]
	v_add_u32_e32 v64, v142, v96
	v_add_u32_e32 v66, v141, v96
	ds_read_b64_tr_b16 v[64:65], v64
	ds_read_b64_tr_b16 v[66:67], v66
	s_waitcnt lgkmcnt(0)
	v_mfma_f32_32x32x16_bf16 v[0:15], v[64:67], v[110:113], v[0:15]
	v_add_u32_e32 v64, v144, v162
	v_add_u32_e32 v66, v143, v162
	ds_read_b64_tr_b16 v[64:65], v64
	ds_read_b64_tr_b16 v[66:67], v66
	s_waitcnt lgkmcnt(0)
	v_mfma_f32_32x32x16_bf16 v[48:63], v[64:67], v[106:109], v[48:63]
	v_add_u32_e32 v64, v144, v163
	v_add_u32_e32 v66, v143, v163
	ds_read_b64_tr_b16 v[64:65], v64
	ds_read_b64_tr_b16 v[66:67], v66
	s_waitcnt lgkmcnt(0)
	v_mfma_f32_32x32x16_bf16 v[32:47], v[64:67], v[106:109], v[32:47]
	v_add_u32_e32 v64, v144, v139
	v_add_u32_e32 v66, v143, v139
	ds_read_b64_tr_b16 v[64:65], v64
	ds_read_b64_tr_b16 v[66:67], v66
	s_waitcnt lgkmcnt(0)
	v_mfma_f32_32x32x16_bf16 v[16:31], v[64:67], v[106:109], v[16:31]
	v_add_u32_e32 v64, v144, v96
	v_add_u32_e32 v66, v143, v96
	ds_read_b64_tr_b16 v[64:65], v64
	ds_read_b64_tr_b16 v[66:67], v66
	s_waitcnt lgkmcnt(0)
	v_mfma_f32_32x32x16_bf16 v[0:15], v[64:67], v[106:109], v[0:15]
	v_add_u32_e32 v64, v146, v162
	v_add_u32_e32 v66, v145, v162
	ds_read_b64_tr_b16 v[64:65], v64
	ds_read_b64_tr_b16 v[66:67], v66
	s_waitcnt lgkmcnt(0)
	v_mfma_f32_32x32x16_bf16 v[48:63], v[64:67], v[102:105], v[48:63]
	v_add_u32_e32 v64, v146, v163
	v_add_u32_e32 v66, v145, v163
	ds_read_b64_tr_b16 v[64:65], v64
	ds_read_b64_tr_b16 v[66:67], v66
	s_waitcnt lgkmcnt(0)
	v_mfma_f32_32x32x16_bf16 v[32:47], v[64:67], v[102:105], v[32:47]
	v_add_u32_e32 v64, v146, v139
	v_add_u32_e32 v66, v145, v139
	ds_read_b64_tr_b16 v[64:65], v64
	ds_read_b64_tr_b16 v[66:67], v66
	s_waitcnt lgkmcnt(0)
	v_mfma_f32_32x32x16_bf16 v[16:31], v[64:67], v[102:105], v[16:31]
	v_add_u32_e32 v64, v146, v96
	v_add_u32_e32 v66, v145, v96
	ds_read_b64_tr_b16 v[64:65], v64
	ds_read_b64_tr_b16 v[66:67], v66
	s_waitcnt lgkmcnt(0)
	v_mfma_f32_32x32x16_bf16 v[0:15], v[64:67], v[102:105], v[0:15]
	v_add_u32_e32 v64, v149, v162
	v_add_u32_e32 v66, v147, v162
	ds_read_b64_tr_b16 v[64:65], v64
	ds_read_b64_tr_b16 v[66:67], v66
	s_waitcnt lgkmcnt(0)
	v_mfma_f32_32x32x16_bf16 v[48:63], v[64:67], v[98:101], v[48:63]
	v_add_u32_e32 v64, v149, v163
	v_add_u32_e32 v66, v147, v163
	ds_read_b64_tr_b16 v[64:65], v64
	ds_read_b64_tr_b16 v[66:67], v66
	s_waitcnt lgkmcnt(0)
	v_mfma_f32_32x32x16_bf16 v[32:47], v[64:67], v[98:101], v[32:47]
	v_add_u32_e32 v64, v149, v139
	v_add_u32_e32 v66, v147, v139
	ds_read_b64_tr_b16 v[64:65], v64
	ds_read_b64_tr_b16 v[66:67], v66
	s_waitcnt lgkmcnt(0)
	v_mfma_f32_32x32x16_bf16 v[16:31], v[64:67], v[98:101], v[16:31]
	v_add_u32_e32 v64, v149, v96
	v_add_u32_e32 v66, v147, v96
	ds_read_b64_tr_b16 v[64:65], v64
	ds_read_b64_tr_b16 v[66:67], v66
	s_waitcnt lgkmcnt(0)
	v_mfma_f32_32x32x16_bf16 v[0:15], v[64:67], v[98:101], v[0:15]
	v_add_u32_e32 v64, v151, v162
	v_add_u32_e32 v66, v150, v162
	ds_read_b64_tr_b16 v[64:65], v64
	ds_read_b64_tr_b16 v[66:67], v66
	s_waitcnt lgkmcnt(0)
	v_mfma_f32_32x32x16_bf16 v[48:63], v[64:67], v[126:129], v[48:63]
	v_add_u32_e32 v64, v151, v163
	v_add_u32_e32 v66, v150, v163
	ds_read_b64_tr_b16 v[64:65], v64
	ds_read_b64_tr_b16 v[66:67], v66
	s_waitcnt lgkmcnt(0)
	v_mfma_f32_32x32x16_bf16 v[32:47], v[64:67], v[126:129], v[32:47]
	v_add_u32_e32 v64, v151, v139
	v_add_u32_e32 v66, v150, v139
	ds_read_b64_tr_b16 v[64:65], v64
	ds_read_b64_tr_b16 v[66:67], v66
	s_waitcnt lgkmcnt(0)
	v_mfma_f32_32x32x16_bf16 v[16:31], v[64:67], v[126:129], v[16:31]
	v_add_u32_e32 v64, v151, v96
	v_add_u32_e32 v66, v150, v96
	ds_read_b64_tr_b16 v[64:65], v64
	ds_read_b64_tr_b16 v[66:67], v66
	s_waitcnt lgkmcnt(0)
	v_mfma_f32_32x32x16_bf16 v[0:15], v[64:67], v[126:129], v[0:15]
	v_add_u32_e32 v64, v153, v162
	v_add_u32_e32 v66, v152, v162
	ds_read_b64_tr_b16 v[64:65], v64
	ds_read_b64_tr_b16 v[66:67], v66
	s_waitcnt lgkmcnt(0)
	v_mfma_f32_32x32x16_bf16 v[48:63], v[64:67], v[122:125], v[48:63]
	v_add_u32_e32 v64, v153, v163
	v_add_u32_e32 v66, v152, v163
	ds_read_b64_tr_b16 v[64:65], v64
	ds_read_b64_tr_b16 v[66:67], v66
	s_waitcnt lgkmcnt(0)
	v_mfma_f32_32x32x16_bf16 v[32:47], v[64:67], v[122:125], v[32:47]
	v_add_u32_e32 v64, v153, v139
	v_add_u32_e32 v66, v152, v139
	ds_read_b64_tr_b16 v[64:65], v64
	ds_read_b64_tr_b16 v[66:67], v66
	s_waitcnt lgkmcnt(0)
	v_mfma_f32_32x32x16_bf16 v[16:31], v[64:67], v[122:125], v[16:31]
	v_add_u32_e32 v64, v153, v96
	v_add_u32_e32 v66, v152, v96
	ds_read_b64_tr_b16 v[64:65], v64
	ds_read_b64_tr_b16 v[66:67], v66
	s_waitcnt lgkmcnt(0)
	v_mfma_f32_32x32x16_bf16 v[0:15], v[64:67], v[122:125], v[0:15]
	v_add_u32_e32 v64, v155, v162
	v_add_u32_e32 v66, v154, v162
	ds_read_b64_tr_b16 v[64:65], v64
	ds_read_b64_tr_b16 v[66:67], v66
	s_waitcnt lgkmcnt(0)
	v_mfma_f32_32x32x16_bf16 v[48:63], v[64:67], v[118:121], v[48:63]
	v_add_u32_e32 v64, v155, v163
	v_add_u32_e32 v66, v154, v163
	ds_read_b64_tr_b16 v[64:65], v64
	ds_read_b64_tr_b16 v[66:67], v66
	s_waitcnt lgkmcnt(0)
	v_mfma_f32_32x32x16_bf16 v[32:47], v[64:67], v[118:121], v[32:47]
	v_add_u32_e32 v64, v155, v139
	v_add_u32_e32 v66, v154, v139
	ds_read_b64_tr_b16 v[64:65], v64
	ds_read_b64_tr_b16 v[66:67], v66
	s_waitcnt lgkmcnt(0)
	v_mfma_f32_32x32x16_bf16 v[16:31], v[64:67], v[118:121], v[16:31]
	v_add_u32_e32 v64, v155, v96
	v_add_u32_e32 v66, v154, v96
	ds_read_b64_tr_b16 v[64:65], v64
	ds_read_b64_tr_b16 v[66:67], v66
	s_waitcnt lgkmcnt(0)
	v_mfma_f32_32x32x16_bf16 v[0:15], v[64:67], v[118:121], v[0:15]
	v_add_u32_e32 v64, v157, v162
	v_add_u32_e32 v66, v156, v162
	ds_read_b64_tr_b16 v[64:65], v64
	ds_read_b64_tr_b16 v[66:67], v66
	s_waitcnt lgkmcnt(0)
	v_mfma_f32_32x32x16_bf16 v[48:63], v[64:67], v[114:117], v[48:63]
	v_add_u32_e32 v64, v157, v163
	v_add_u32_e32 v66, v156, v163
	ds_read_b64_tr_b16 v[64:65], v64
	ds_read_b64_tr_b16 v[66:67], v66
	s_nop 7
	v_pk_mul_f32 v[48:49], v[130:131], v[48:49] op_sel_hi:[0,1]
	s_waitcnt lgkmcnt(0)
	v_mfma_f32_32x32x16_bf16 v[32:47], v[64:67], v[114:117], v[32:47]
	v_add_u32_e32 v64, v157, v139
	v_add_u32_e32 v66, v156, v139
	ds_read_b64_tr_b16 v[64:65], v64
	ds_read_b64_tr_b16 v[66:67], v66
	v_mul_f32_e64 v50, v130, v50
	v_mul_f32_e64 v51, v130, v51
	v_cvt_pk_bf16_f32 v48, v48, v49
	v_cvt_pk_bf16_f32 v49, v50, v51
	s_waitcnt lgkmcnt(0)
	v_mfma_f32_32x32x16_bf16 v[16:31], v[64:67], v[114:117], v[16:31]
	v_add_u32_e32 v64, v157, v96
	v_add_u32_e32 v66, v156, v96
	ds_read_b64_tr_b16 v[64:65], v64
	ds_read_b64_tr_b16 v[66:67], v66
	ds_write_b64 v158, v[48:49]
	v_pk_mul_f32 v[48:49], v[130:131], v[52:53] op_sel_hi:[0,1]
	v_pk_mul_f32 v[50:51], v[130:131], v[54:55] op_sel_hi:[0,1]
	v_cvt_pk_bf16_f32 v48, v48, v49
	v_cvt_pk_bf16_f32 v49, v50, v51
	ds_write_b64 v159, v[48:49]
	v_pk_mul_f32 v[48:49], v[130:131], v[56:57] op_sel_hi:[0,1]
	v_pk_mul_f32 v[50:51], v[130:131], v[58:59] op_sel_hi:[0,1]
	v_cvt_pk_bf16_f32 v48, v48, v49
	v_cvt_pk_bf16_f32 v49, v50, v51
	ds_write_b64 v160, v[48:49]
	v_pk_mul_f32 v[48:49], v[130:131], v[60:61] op_sel_hi:[0,1]
	v_pk_mul_f32 v[50:51], v[130:131], v[62:63] op_sel_hi:[0,1]
	v_cvt_pk_bf16_f32 v48, v48, v49
	v_cvt_pk_bf16_f32 v49, v50, v51
	ds_write_b64 v161, v[48:49]
	ds_read_b128 v[48:51], v148
	v_pk_mul_f32 v[32:33], v[130:131], v[32:33] op_sel_hi:[0,1]
	v_pk_mul_f32 v[34:35], v[130:131], v[34:35] op_sel_hi:[0,1]
	v_cvt_pk_bf16_f32 v32, v32, v33
	v_cvt_pk_bf16_f32 v33, v34, v35
	s_waitcnt lgkmcnt(0)
	global_store_dwordx4 v[134:135], v[48:51], off offset:256 sc1
	ds_read_b128 v[48:51], v140
	ds_write_b64 v158, v[32:33]
	v_pk_mul_f32 v[32:33], v[130:131], v[36:37] op_sel_hi:[0,1]
	v_pk_mul_f32 v[34:35], v[130:131], v[38:39] op_sel_hi:[0,1]
	v_cvt_pk_bf16_f32 v32, v32, v33
	v_cvt_pk_bf16_f32 v33, v34, v35
	ds_write_b64 v159, v[32:33]
	v_pk_mul_f32 v[32:33], v[130:131], v[40:41] op_sel_hi:[0,1]
	v_pk_mul_f32 v[34:35], v[130:131], v[42:43] op_sel_hi:[0,1]
	v_cvt_pk_bf16_f32 v32, v32, v33
	v_cvt_pk_bf16_f32 v33, v34, v35
	ds_write_b64 v160, v[32:33]
	v_pk_mul_f32 v[32:33], v[130:131], v[44:45] op_sel_hi:[0,1]
	v_pk_mul_f32 v[34:35], v[130:131], v[46:47] op_sel_hi:[0,1]
	v_cvt_pk_bf16_f32 v32, v32, v33
	v_cvt_pk_bf16_f32 v33, v34, v35
	ds_write_b64 v161, v[32:33]
	ds_read_b128 v[32:35], v148
	v_pk_mul_f32 v[16:17], v[130:131], v[16:17] op_sel_hi:[0,1]
	v_pk_mul_f32 v[18:19], v[130:131], v[18:19] op_sel_hi:[0,1]
	v_cvt_pk_bf16_f32 v16, v16, v17
	v_cvt_pk_bf16_f32 v17, v18, v19
	s_waitcnt lgkmcnt(0)
	global_store_dwordx4 v[134:135], v[32:35], off offset:320 sc1
	ds_read_b128 v[32:35], v140
	ds_write_b64 v158, v[16:17]
	v_pk_mul_f32 v[16:17], v[130:131], v[20:21] op_sel_hi:[0,1]
	v_pk_mul_f32 v[18:19], v[130:131], v[22:23] op_sel_hi:[0,1]
	v_cvt_pk_bf16_f32 v16, v16, v17
	v_cvt_pk_bf16_f32 v17, v18, v19
	v_mfma_f32_32x32x16_bf16 v[0:15], v[64:67], v[114:117], v[0:15]
	ds_write_b64 v159, v[16:17]
	v_mul_f32_e64 v16, v130, v24
	v_mul_f32_e64 v17, v130, v25
	v_mul_f32_e64 v18, v130, v26
	v_mul_f32_e64 v19, v130, v27
	v_cvt_pk_bf16_f32 v16, v16, v17
	v_cvt_pk_bf16_f32 v17, v18, v19
	ds_write_b64 v160, v[16:17]
	v_pk_mul_f32 v[16:17], v[130:131], v[28:29] op_sel_hi:[0,1]
	v_pk_mul_f32 v[18:19], v[130:131], v[30:31] op_sel_hi:[0,1]
	v_cvt_pk_bf16_f32 v16, v16, v17
	v_cvt_pk_bf16_f32 v17, v18, v19
	ds_write_b64 v161, v[16:17]
	ds_read_b128 v[16:19], v148
	v_pk_mul_f32 v[0:1], v[130:131], v[0:1] op_sel_hi:[0,1]
	v_pk_mul_f32 v[2:3], v[130:131], v[2:3] op_sel_hi:[0,1]
	v_cvt_pk_bf16_f32 v0, v0, v1
	v_cvt_pk_bf16_f32 v1, v2, v3
	s_waitcnt lgkmcnt(0)
	global_store_dwordx4 v[134:135], v[16:19], off offset:384 sc1
	ds_read_b128 v[16:19], v140
	ds_write_b64 v158, v[0:1]
	v_pk_mul_f32 v[0:1], v[130:131], v[4:5] op_sel_hi:[0,1]
	v_pk_mul_f32 v[2:3], v[130:131], v[6:7] op_sel_hi:[0,1]
	v_cvt_pk_bf16_f32 v0, v0, v1
	v_cvt_pk_bf16_f32 v1, v2, v3
	ds_write_b64 v159, v[0:1]
	v_pk_mul_f32 v[0:1], v[130:131], v[8:9] op_sel_hi:[0,1]
	v_pk_mul_f32 v[2:3], v[130:131], v[10:11] op_sel_hi:[0,1]
	v_cvt_pk_bf16_f32 v0, v0, v1
	v_cvt_pk_bf16_f32 v1, v2, v3
	ds_write_b64 v160, v[0:1]
	v_pk_mul_f32 v[0:1], v[130:131], v[12:13] op_sel_hi:[0,1]
	v_pk_mul_f32 v[2:3], v[130:131], v[14:15] op_sel_hi:[0,1]
	v_cvt_pk_bf16_f32 v0, v0, v1
	v_cvt_pk_bf16_f32 v1, v2, v3
	ds_write_b64 v161, v[0:1]
	ds_read_b128 v[0:3], v148
	global_store_dwordx4 v[132:133], v[48:51], off offset:256 sc1
	global_store_dwordx4 v[132:133], v[32:35], off offset:320 sc1
	s_waitcnt lgkmcnt(5)
	global_store_dwordx4 v[132:133], v[16:19], off offset:384 sc1
	s_waitcnt lgkmcnt(0)
	global_store_dwordx4 v[134:135], v[0:3], off offset:448 sc1
	ds_read_b128 v[0:3], v140
	s_waitcnt lgkmcnt(0)
	global_store_dwordx4 v[132:133], v[0:3], off offset:448 sc1
	s_barrier
